# v51 + the ten K-loop head labels aligned to 64 B (.p2align 6)
# speedup vs baseline: 1.0052x; 1.0052x over previous
.LBB0_140:
	v_mov_b32_e32 v123, 0
	s_and_b64 vcc, exec, s[0:1]
	v_mov_b32_e32 v122, v123
	v_mov_b32_e32 v121, v123
	v_mov_b32_e32 v120, v123
	v_mov_b32_e32 v119, v123
	v_mov_b32_e32 v118, v123
	v_mov_b32_e32 v117, v123
	v_mov_b32_e32 v116, v123
	v_mov_b32_e32 v111, v123
	v_mov_b32_e32 v110, v123
	v_mov_b32_e32 v109, v123
	v_mov_b32_e32 v108, v123
	v_mov_b32_e32 v103, v123
	v_mov_b32_e32 v102, v123
	v_mov_b32_e32 v101, v123
	v_mov_b32_e32 v100, v123
	v_mov_b32_e32 v95, v123
	v_mov_b32_e32 v94, v123
	v_mov_b32_e32 v93, v123
	v_mov_b32_e32 v92, v123
	v_mov_b32_e32 v87, v123
	v_mov_b32_e32 v86, v123
	v_mov_b32_e32 v85, v123
	v_mov_b32_e32 v84, v123
	v_mov_b32_e32 v79, v123
	v_mov_b32_e32 v78, v123
	v_mov_b32_e32 v77, v123
	v_mov_b32_e32 v76, v123
	v_mov_b32_e32 v71, v123
	v_mov_b32_e32 v70, v123
	v_mov_b32_e32 v69, v123
	v_mov_b32_e32 v68, v123
	v_mov_b32_e32 v127, v123
	v_mov_b32_e32 v126, v123
	v_mov_b32_e32 v125, v123
	v_mov_b32_e32 v124, v123
	v_mov_b32_e32 v115, v123
	v_mov_b32_e32 v114, v123
	v_mov_b32_e32 v113, v123
	v_mov_b32_e32 v112, v123
	v_mov_b32_e32 v107, v123
	v_mov_b32_e32 v106, v123
	v_mov_b32_e32 v105, v123
	v_mov_b32_e32 v104, v123
	v_mov_b32_e32 v99, v123
	v_mov_b32_e32 v98, v123
	v_mov_b32_e32 v97, v123
	v_mov_b32_e32 v96, v123
	v_mov_b32_e32 v91, v123
	v_mov_b32_e32 v90, v123
	v_mov_b32_e32 v89, v123
	v_mov_b32_e32 v88, v123
	v_mov_b32_e32 v83, v123
	v_mov_b32_e32 v82, v123
	v_mov_b32_e32 v81, v123
	v_mov_b32_e32 v80, v123
	v_mov_b32_e32 v75, v123
	v_mov_b32_e32 v74, v123
	v_mov_b32_e32 v73, v123
	v_mov_b32_e32 v72, v123
	v_mov_b32_e32 v67, v123
	v_mov_b32_e32 v66, v123
	v_mov_b32_e32 v65, v123
	v_mov_b32_e32 v64, v123
	v_mov_b32_e32 v63, v123
	v_mov_b32_e32 v62, v123
	v_mov_b32_e32 v61, v123
	v_mov_b32_e32 v60, v123
	v_mov_b32_e32 v55, v123
	v_mov_b32_e32 v54, v123
	v_mov_b32_e32 v53, v123
	v_mov_b32_e32 v52, v123
	v_mov_b32_e32 v47, v123
	v_mov_b32_e32 v46, v123
	v_mov_b32_e32 v45, v123
	v_mov_b32_e32 v44, v123
	v_mov_b32_e32 v39, v123
	v_mov_b32_e32 v38, v123
	v_mov_b32_e32 v37, v123
	v_mov_b32_e32 v36, v123
	v_mov_b32_e32 v31, v123
	v_mov_b32_e32 v30, v123
	v_mov_b32_e32 v29, v123
	v_mov_b32_e32 v28, v123
	v_mov_b32_e32 v23, v123
	v_mov_b32_e32 v22, v123
	v_mov_b32_e32 v21, v123
	v_mov_b32_e32 v20, v123
	v_mov_b32_e32 v15, v123
	v_mov_b32_e32 v14, v123
	v_mov_b32_e32 v13, v123
	v_mov_b32_e32 v12, v123
	v_mov_b32_e32 v7, v123
	v_mov_b32_e32 v6, v123
	v_mov_b32_e32 v5, v123
	v_mov_b32_e32 v4, v123
	v_mov_b32_e32 v59, v123
	v_mov_b32_e32 v58, v123
	v_mov_b32_e32 v57, v123
	v_mov_b32_e32 v56, v123
	v_mov_b32_e32 v51, v123
	v_mov_b32_e32 v50, v123
	v_mov_b32_e32 v49, v123
	v_mov_b32_e32 v48, v123
	v_mov_b32_e32 v43, v123
	v_mov_b32_e32 v42, v123
	v_mov_b32_e32 v41, v123
	v_mov_b32_e32 v40, v123
	v_mov_b32_e32 v35, v123
	v_mov_b32_e32 v34, v123
	v_mov_b32_e32 v33, v123
	v_mov_b32_e32 v32, v123
	v_mov_b32_e32 v27, v123
	v_mov_b32_e32 v26, v123
	v_mov_b32_e32 v25, v123
	v_mov_b32_e32 v24, v123
	v_mov_b32_e32 v19, v123
	v_mov_b32_e32 v18, v123
	v_mov_b32_e32 v17, v123
	v_mov_b32_e32 v16, v123
	v_mov_b32_e32 v11, v123
	v_mov_b32_e32 v10, v123
	v_mov_b32_e32 v9, v123
	v_mov_b32_e32 v8, v123
	v_mov_b32_e32 v3, v123
	v_mov_b32_e32 v2, v123
	v_mov_b32_e32 v1, v123
	v_mov_b32_e32 v0, v123
	s_cbranch_vccnz .LBB0_143
	s_add_u32 s20, s20, 0x80
	s_addc_u32 s21, s21, 0
	s_add_u32 s52, s22, 0x100
	v_mov_b32_e32 v0, 0
	s_addc_u32 s53, s23, 0
	s_mov_b32 s22, 0
	v_mov_b32_e32 v1, v0
	v_mov_b32_e32 v2, v0
	v_mov_b32_e32 v3, v0
	v_mov_b32_e32 v8, v0
	v_mov_b32_e32 v9, v0
	v_mov_b32_e32 v10, v0
	v_mov_b32_e32 v11, v0
	v_mov_b32_e32 v16, v0
	v_mov_b32_e32 v17, v0
	v_mov_b32_e32 v18, v0
	v_mov_b32_e32 v19, v0
	v_mov_b32_e32 v24, v0
	v_mov_b32_e32 v25, v0
	v_mov_b32_e32 v26, v0
	v_mov_b32_e32 v27, v0
	v_mov_b32_e32 v32, v0
	v_mov_b32_e32 v33, v0
	v_mov_b32_e32 v34, v0
	v_mov_b32_e32 v35, v0
	v_mov_b32_e32 v40, v0
	v_mov_b32_e32 v41, v0
	v_mov_b32_e32 v42, v0
	v_mov_b32_e32 v43, v0
	v_mov_b32_e32 v48, v0
	v_mov_b32_e32 v49, v0
	v_mov_b32_e32 v50, v0
	v_mov_b32_e32 v51, v0
	v_mov_b32_e32 v56, v0
	v_mov_b32_e32 v57, v0
	v_mov_b32_e32 v58, v0
	v_mov_b32_e32 v59, v0
	v_mov_b32_e32 v4, v0
	v_mov_b32_e32 v5, v0
	v_mov_b32_e32 v6, v0
	v_mov_b32_e32 v7, v0
	v_mov_b32_e32 v12, v0
	v_mov_b32_e32 v13, v0
	v_mov_b32_e32 v14, v0
	v_mov_b32_e32 v15, v0
	v_mov_b32_e32 v20, v0
	v_mov_b32_e32 v21, v0
	v_mov_b32_e32 v22, v0
	v_mov_b32_e32 v23, v0
	v_mov_b32_e32 v28, v0
	v_mov_b32_e32 v29, v0
	v_mov_b32_e32 v30, v0
	v_mov_b32_e32 v31, v0
	v_mov_b32_e32 v36, v0
	v_mov_b32_e32 v37, v0
	v_mov_b32_e32 v38, v0
	v_mov_b32_e32 v39, v0
	v_mov_b32_e32 v44, v0
	v_mov_b32_e32 v45, v0
	v_mov_b32_e32 v46, v0
	v_mov_b32_e32 v47, v0
	v_mov_b32_e32 v52, v0
	v_mov_b32_e32 v53, v0
	v_mov_b32_e32 v54, v0
	v_mov_b32_e32 v55, v0
	v_mov_b32_e32 v60, v0
	v_mov_b32_e32 v61, v0
	v_mov_b32_e32 v62, v0
	v_mov_b32_e32 v63, v0
	v_mov_b32_e32 v64, v0
	v_mov_b32_e32 v65, v0
	v_mov_b32_e32 v66, v0
	v_mov_b32_e32 v67, v0
	v_mov_b32_e32 v72, v0
	v_mov_b32_e32 v73, v0
	v_mov_b32_e32 v74, v0
	v_mov_b32_e32 v75, v0
	v_mov_b32_e32 v80, v0
	v_mov_b32_e32 v81, v0
	v_mov_b32_e32 v82, v0
	v_mov_b32_e32 v83, v0
	v_mov_b32_e32 v88, v0
	v_mov_b32_e32 v89, v0
	v_mov_b32_e32 v90, v0
	v_mov_b32_e32 v91, v0
	v_mov_b32_e32 v96, v0
	v_mov_b32_e32 v97, v0
	v_mov_b32_e32 v98, v0
	v_mov_b32_e32 v99, v0
	v_mov_b32_e32 v104, v0
	v_mov_b32_e32 v105, v0
	v_mov_b32_e32 v106, v0
	v_mov_b32_e32 v107, v0
	v_mov_b32_e32 v112, v0
	v_mov_b32_e32 v113, v0
	v_mov_b32_e32 v114, v0
	v_mov_b32_e32 v115, v0
	v_mov_b32_e32 v124, v0
	v_mov_b32_e32 v125, v0
	v_mov_b32_e32 v126, v0
	v_mov_b32_e32 v127, v0
	v_mov_b32_e32 v68, v0
	v_mov_b32_e32 v69, v0
	v_mov_b32_e32 v70, v0
	v_mov_b32_e32 v71, v0
	v_mov_b32_e32 v76, v0
	v_mov_b32_e32 v77, v0
	v_mov_b32_e32 v78, v0
	v_mov_b32_e32 v79, v0
	v_mov_b32_e32 v84, v0
	v_mov_b32_e32 v85, v0
	v_mov_b32_e32 v86, v0
	v_mov_b32_e32 v87, v0
	v_mov_b32_e32 v92, v0
	v_mov_b32_e32 v93, v0
	v_mov_b32_e32 v94, v0
	v_mov_b32_e32 v95, v0
	v_mov_b32_e32 v100, v0
	v_mov_b32_e32 v101, v0
	v_mov_b32_e32 v102, v0
	v_mov_b32_e32 v103, v0
	v_mov_b32_e32 v108, v0
	v_mov_b32_e32 v109, v0
	v_mov_b32_e32 v110, v0
	v_mov_b32_e32 v111, v0
	v_mov_b32_e32 v116, v0
	v_mov_b32_e32 v117, v0
	v_mov_b32_e32 v118, v0
	v_mov_b32_e32 v119, v0
	v_mov_b32_e32 v120, v0
	v_mov_b32_e32 v121, v0
	v_mov_b32_e32 v122, v0
	v_mov_b32_e32 v123, v0
	.p2align 6

.LBB0_226:
	v_mov_b32_e32 v201, 0
	s_andn2_b64 vcc, exec, s[16:17]
	v_mov_b32_e32 v200, 0
	v_mov_b32_e32 v203, 0
	v_mov_b32_e32 v202, 0
	v_mov_b32_e32 v205, 0
	v_mov_b32_e32 v204, 0
	v_mov_b32_e32 v207, 0
	v_mov_b32_e32 v206, 0
	v_mov_b32_e32 v195, 0
	v_mov_b32_e32 v194, 0
	v_mov_b32_e32 v193, 0
	v_mov_b32_e32 v192, 0
	v_mov_b32_e32 v191, 0
	v_mov_b32_e32 v190, 0
	v_mov_b32_e32 v189, 0
	v_mov_b32_e32 v188, 0
	v_mov_b32_e32 v179, 0
	v_mov_b32_e32 v178, 0
	v_mov_b32_e32 v177, 0
	v_mov_b32_e32 v176, 0
	v_mov_b32_e32 v175, 0
	v_mov_b32_e32 v174, 0
	v_mov_b32_e32 v173, 0
	v_mov_b32_e32 v172, 0
	v_mov_b32_e32 v161, 0
	v_mov_b32_e32 v160, 0
	v_mov_b32_e32 v159, 0
	v_mov_b32_e32 v158, 0
	v_mov_b32_e32 v157, 0
	v_mov_b32_e32 v156, 0
	v_mov_b32_e32 v155, 0
	v_mov_b32_e32 v154, 0
	v_mov_b32_e32 v211, 0
	v_mov_b32_e32 v210, 0
	v_mov_b32_e32 v209, 0
	v_mov_b32_e32 v208, 0
	v_mov_b32_e32 v199, 0
	v_mov_b32_e32 v198, 0
	v_mov_b32_e32 v197, 0
	v_mov_b32_e32 v196, 0
	v_mov_b32_e32 v187, 0
	v_mov_b32_e32 v186, 0
	v_mov_b32_e32 v185, 0
	v_mov_b32_e32 v184, 0
	v_mov_b32_e32 v183, 0
	v_mov_b32_e32 v182, 0
	v_mov_b32_e32 v181, 0
	v_mov_b32_e32 v180, 0
	v_mov_b32_e32 v171, 0
	v_mov_b32_e32 v170, 0
	v_mov_b32_e32 v169, 0
	v_mov_b32_e32 v168, 0
	v_mov_b32_e32 v167, 0
	v_mov_b32_e32 v166, 0
	v_mov_b32_e32 v165, 0
	v_mov_b32_e32 v164, 0
	v_mov_b32_e32 v153, 0
	v_mov_b32_e32 v152, 0
	v_mov_b32_e32 v151, 0
	v_mov_b32_e32 v150, 0
	v_mov_b32_e32 v149, 0
	v_mov_b32_e32 v148, 0
	v_mov_b32_e32 v147, 0
	v_mov_b32_e32 v146, 0
	v_mov_b32_e32 v145, 0
	v_mov_b32_e32 v144, 0
	v_mov_b32_e32 v143, 0
	v_mov_b32_e32 v142, 0
	v_mov_b32_e32 v127, 0
	v_mov_b32_e32 v126, 0
	v_mov_b32_e32 v125, 0
	v_mov_b32_e32 v124, 0
	v_mov_b32_e32 v115, 0
	v_mov_b32_e32 v114, 0
	v_mov_b32_e32 v113, 0
	v_mov_b32_e32 v112, 0
	v_mov_b32_e32 v111, 0
	v_mov_b32_e32 v110, 0
	v_mov_b32_e32 v109, 0
	v_mov_b32_e32 v108, 0
	v_mov_b32_e32 v99, 0
	v_mov_b32_e32 v98, 0
	v_mov_b32_e32 v97, 0
	v_mov_b32_e32 v96, 0
	v_mov_b32_e32 v95, 0
	v_mov_b32_e32 v94, 0
	v_mov_b32_e32 v93, 0
	v_mov_b32_e32 v92, 0
	v_mov_b32_e32 v83, 0
	v_mov_b32_e32 v82, 0
	v_mov_b32_e32 v81, 0
	v_mov_b32_e32 v80, 0
	v_mov_b32_e32 v79, 0
	v_mov_b32_e32 v78, 0
	v_mov_b32_e32 v77, 0
	v_mov_b32_e32 v76, 0
	v_mov_b32_e32 v123, 0
	v_mov_b32_e32 v122, 0
	v_mov_b32_e32 v121, 0
	v_mov_b32_e32 v120, 0
	v_mov_b32_e32 v119, 0
	v_mov_b32_e32 v118, 0
	v_mov_b32_e32 v117, 0
	v_mov_b32_e32 v116, 0
	v_mov_b32_e32 v107, 0
	v_mov_b32_e32 v106, 0
	v_mov_b32_e32 v105, 0
	v_mov_b32_e32 v104, 0
	v_mov_b32_e32 v103, 0
	v_mov_b32_e32 v102, 0
	v_mov_b32_e32 v101, 0
	v_mov_b32_e32 v100, 0
	v_mov_b32_e32 v91, 0
	v_mov_b32_e32 v90, 0
	v_mov_b32_e32 v89, 0
	v_mov_b32_e32 v88, 0
	v_mov_b32_e32 v87, 0
	v_mov_b32_e32 v86, 0
	v_mov_b32_e32 v85, 0
	v_mov_b32_e32 v84, 0
	v_mov_b32_e32 v75, 0
	v_mov_b32_e32 v74, 0
	v_mov_b32_e32 v73, 0
	v_mov_b32_e32 v72, 0
	v_mov_b32_e32 v71, 0
	v_mov_b32_e32 v70, 0
	v_mov_b32_e32 v69, 0
	v_mov_b32_e32 v68, 0
	s_cbranch_vccnz .LBB0_230
	s_add_u32 s24, s24, 0xc000
	s_addc_u32 s25, s25, 0
	s_add_u32 s60, s26, 0x10000
	v_mov_b32_e32 v0, 0
	s_addc_u32 s61, s27, 0
	s_mov_b32 s26, 0
	s_waitcnt lgkmcnt(0)
	v_mov_b32_e32 v1, v0
	v_mov_b32_e32 v2, v0
	v_mov_b32_e32 v3, v0
	v_mov_b32_e32 v4, v0
	v_mov_b32_e32 v5, v0
	v_mov_b32_e32 v6, v0
	v_mov_b32_e32 v7, v0
	v_mov_b32_e32 v8, v0
	v_mov_b32_e32 v9, v0
	v_mov_b32_e32 v10, v0
	v_mov_b32_e32 v11, v0
	v_mov_b32_e32 v12, v0
	v_mov_b32_e32 v13, v0
	v_mov_b32_e32 v14, v0
	v_mov_b32_e32 v15, v0
	v_mov_b32_e32 v20, v0
	v_mov_b32_e32 v21, v0
	v_mov_b32_e32 v22, v0
	v_mov_b32_e32 v23, v0
	v_mov_b32_e32 v28, v0
	v_mov_b32_e32 v29, v0
	v_mov_b32_e32 v30, v0
	v_mov_b32_e32 v31, v0
	v_mov_b32_e32 v36, v0
	v_mov_b32_e32 v37, v0
	v_mov_b32_e32 v38, v0
	v_mov_b32_e32 v39, v0
	v_mov_b32_e32 v44, v0
	v_mov_b32_e32 v45, v0
	v_mov_b32_e32 v46, v0
	v_mov_b32_e32 v47, v0
	v_mov_b32_e32 v16, v0
	v_mov_b32_e32 v17, v0
	v_mov_b32_e32 v18, v0
	v_mov_b32_e32 v19, v0
	v_mov_b32_e32 v24, v0
	v_mov_b32_e32 v25, v0
	v_mov_b32_e32 v26, v0
	v_mov_b32_e32 v27, v0
	v_mov_b32_e32 v32, v0
	v_mov_b32_e32 v33, v0
	v_mov_b32_e32 v34, v0
	v_mov_b32_e32 v35, v0
	v_mov_b32_e32 v40, v0
	v_mov_b32_e32 v41, v0
	v_mov_b32_e32 v42, v0
	v_mov_b32_e32 v43, v0
	v_mov_b32_e32 v48, v0
	v_mov_b32_e32 v49, v0
	v_mov_b32_e32 v50, v0
	v_mov_b32_e32 v51, v0
	v_mov_b32_e32 v52, v0
	v_mov_b32_e32 v53, v0
	v_mov_b32_e32 v54, v0
	v_mov_b32_e32 v55, v0
	v_mov_b32_e32 v56, v0
	v_mov_b32_e32 v57, v0
	v_mov_b32_e32 v58, v0
	v_mov_b32_e32 v59, v0
	v_mov_b32_e32 v60, v0
	v_mov_b32_e32 v61, v0
	v_mov_b32_e32 v62, v0
	v_mov_b32_e32 v63, v0
	v_mov_b32_e32 v64, v0
	v_mov_b32_e32 v65, v0
	v_mov_b32_e32 v66, v0
	v_mov_b32_e32 v67, v0
	v_mov_b32_e32 v68, v0
	v_mov_b32_e32 v69, v0
	v_mov_b32_e32 v70, v0
	v_mov_b32_e32 v71, v0
	v_mov_b32_e32 v72, v0
	v_mov_b32_e32 v73, v0
	v_mov_b32_e32 v74, v0
	v_mov_b32_e32 v75, v0
	v_mov_b32_e32 v76, v0
	v_mov_b32_e32 v77, v0
	v_mov_b32_e32 v78, v0
	v_mov_b32_e32 v79, v0
	v_mov_b32_e32 v84, v0
	v_mov_b32_e32 v85, v0
	v_mov_b32_e32 v86, v0
	v_mov_b32_e32 v87, v0
	v_mov_b32_e32 v92, v0
	v_mov_b32_e32 v93, v0
	v_mov_b32_e32 v94, v0
	v_mov_b32_e32 v95, v0
	v_mov_b32_e32 v100, v0
	v_mov_b32_e32 v101, v0
	v_mov_b32_e32 v102, v0
	v_mov_b32_e32 v103, v0
	v_mov_b32_e32 v108, v0
	v_mov_b32_e32 v109, v0
	v_mov_b32_e32 v110, v0
	v_mov_b32_e32 v111, v0
	v_mov_b32_e32 v80, v0
	v_mov_b32_e32 v81, v0
	v_mov_b32_e32 v82, v0
	v_mov_b32_e32 v83, v0
	v_mov_b32_e32 v88, v0
	v_mov_b32_e32 v89, v0
	v_mov_b32_e32 v90, v0
	v_mov_b32_e32 v91, v0
	v_mov_b32_e32 v96, v0
	v_mov_b32_e32 v97, v0
	v_mov_b32_e32 v98, v0
	v_mov_b32_e32 v99, v0
	v_mov_b32_e32 v104, v0
	v_mov_b32_e32 v105, v0
	v_mov_b32_e32 v106, v0
	v_mov_b32_e32 v107, v0
	v_mov_b32_e32 v112, v0
	v_mov_b32_e32 v113, v0
	v_mov_b32_e32 v114, v0
	v_mov_b32_e32 v115, v0
	v_mov_b32_e32 v116, v0
	v_mov_b32_e32 v117, v0
	v_mov_b32_e32 v118, v0
	v_mov_b32_e32 v119, v0
	v_mov_b32_e32 v120, v0
	v_mov_b32_e32 v121, v0
	v_mov_b32_e32 v122, v0
	v_mov_b32_e32 v123, v0
	v_mov_b32_e32 v124, v0
	v_mov_b32_e32 v125, v0
	v_mov_b32_e32 v126, v0
	v_mov_b32_e32 v127, v0
	.p2align 6

.LBB0_321:
	v_mov_b32_e32 v127, 0
	s_andn2_b64 vcc, exec, s[38:39]
	v_mov_b32_e32 v126, v127
	v_mov_b32_e32 v125, v127
	v_mov_b32_e32 v124, v127
	v_mov_b32_e32 v123, v127
	v_mov_b32_e32 v122, v127
	v_mov_b32_e32 v121, v127
	v_mov_b32_e32 v120, v127
	v_mov_b32_e32 v111, v127
	v_mov_b32_e32 v110, v127
	v_mov_b32_e32 v109, v127
	v_mov_b32_e32 v108, v127
	v_mov_b32_e32 v107, v127
	v_mov_b32_e32 v106, v127
	v_mov_b32_e32 v105, v127
	v_mov_b32_e32 v104, v127
	v_mov_b32_e32 v95, v127
	v_mov_b32_e32 v94, v127
	v_mov_b32_e32 v93, v127
	v_mov_b32_e32 v92, v127
	v_mov_b32_e32 v91, v127
	v_mov_b32_e32 v90, v127
	v_mov_b32_e32 v89, v127
	v_mov_b32_e32 v88, v127
	v_mov_b32_e32 v79, v127
	v_mov_b32_e32 v78, v127
	v_mov_b32_e32 v77, v127
	v_mov_b32_e32 v76, v127
	v_mov_b32_e32 v75, v127
	v_mov_b32_e32 v74, v127
	v_mov_b32_e32 v73, v127
	v_mov_b32_e32 v72, v127
	v_mov_b32_e32 v119, v127
	v_mov_b32_e32 v118, v127
	v_mov_b32_e32 v117, v127
	v_mov_b32_e32 v116, v127
	v_mov_b32_e32 v115, v127
	v_mov_b32_e32 v114, v127
	v_mov_b32_e32 v113, v127
	v_mov_b32_e32 v112, v127
	v_mov_b32_e32 v103, v127
	v_mov_b32_e32 v102, v127
	v_mov_b32_e32 v101, v127
	v_mov_b32_e32 v100, v127
	v_mov_b32_e32 v99, v127
	v_mov_b32_e32 v98, v127
	v_mov_b32_e32 v97, v127
	v_mov_b32_e32 v96, v127
	v_mov_b32_e32 v87, v127
	v_mov_b32_e32 v86, v127
	v_mov_b32_e32 v85, v127
	v_mov_b32_e32 v84, v127
	v_mov_b32_e32 v83, v127
	v_mov_b32_e32 v82, v127
	v_mov_b32_e32 v81, v127
	v_mov_b32_e32 v80, v127
	v_mov_b32_e32 v71, v127
	v_mov_b32_e32 v70, v127
	v_mov_b32_e32 v69, v127
	v_mov_b32_e32 v68, v127
	v_mov_b32_e32 v67, v127
	v_mov_b32_e32 v66, v127
	v_mov_b32_e32 v65, v127
	v_mov_b32_e32 v64, v127
	v_mov_b32_e32 v63, v127
	v_mov_b32_e32 v62, v127
	v_mov_b32_e32 v61, v127
	v_mov_b32_e32 v60, v127
	v_mov_b32_e32 v59, v127
	v_mov_b32_e32 v58, v127
	v_mov_b32_e32 v57, v127
	v_mov_b32_e32 v56, v127
	v_mov_b32_e32 v47, v127
	v_mov_b32_e32 v46, v127
	v_mov_b32_e32 v45, v127
	v_mov_b32_e32 v44, v127
	v_mov_b32_e32 v43, v127
	v_mov_b32_e32 v42, v127
	v_mov_b32_e32 v41, v127
	v_mov_b32_e32 v40, v127
	v_mov_b32_e32 v31, v127
	v_mov_b32_e32 v30, v127
	v_mov_b32_e32 v29, v127
	v_mov_b32_e32 v28, v127
	v_mov_b32_e32 v27, v127
	v_mov_b32_e32 v26, v127
	v_mov_b32_e32 v25, v127
	v_mov_b32_e32 v24, v127
	v_mov_b32_e32 v15, v127
	v_mov_b32_e32 v14, v127
	v_mov_b32_e32 v13, v127
	v_mov_b32_e32 v12, v127
	v_mov_b32_e32 v11, v127
	v_mov_b32_e32 v10, v127
	v_mov_b32_e32 v9, v127
	v_mov_b32_e32 v8, v127
	v_mov_b32_e32 v55, v127
	v_mov_b32_e32 v54, v127
	v_mov_b32_e32 v53, v127
	v_mov_b32_e32 v52, v127
	v_mov_b32_e32 v51, v127
	v_mov_b32_e32 v50, v127
	v_mov_b32_e32 v49, v127
	v_mov_b32_e32 v48, v127
	v_mov_b32_e32 v39, v127
	v_mov_b32_e32 v38, v127
	v_mov_b32_e32 v37, v127
	v_mov_b32_e32 v36, v127
	v_mov_b32_e32 v35, v127
	v_mov_b32_e32 v34, v127
	v_mov_b32_e32 v33, v127
	v_mov_b32_e32 v32, v127
	v_mov_b32_e32 v23, v127
	v_mov_b32_e32 v22, v127
	v_mov_b32_e32 v21, v127
	v_mov_b32_e32 v20, v127
	v_mov_b32_e32 v19, v127
	v_mov_b32_e32 v18, v127
	v_mov_b32_e32 v17, v127
	v_mov_b32_e32 v16, v127
	v_mov_b32_e32 v7, v127
	v_mov_b32_e32 v6, v127
	v_mov_b32_e32 v5, v127
	v_mov_b32_e32 v4, v127
	v_mov_b32_e32 v3, v127
	v_mov_b32_e32 v2, v127
	v_mov_b32_e32 v1, v127
	v_mov_b32_e32 v0, v127
	s_cbranch_vccnz .LBB0_324
	s_add_u32 s0, s52, 0x80
	s_addc_u32 s1, s53, 0
	s_add_u32 s33, s50, 0x100
	v_mov_b32_e32 v0, 0
	s_addc_u32 s52, s51, 0
	s_mov_b32 s50, 0
	v_mov_b32_e32 v1, v0
	v_mov_b32_e32 v2, v0
	v_mov_b32_e32 v3, v0
	v_mov_b32_e32 v4, v0
	v_mov_b32_e32 v5, v0
	v_mov_b32_e32 v6, v0
	v_mov_b32_e32 v7, v0
	v_mov_b32_e32 v16, v0
	v_mov_b32_e32 v17, v0
	v_mov_b32_e32 v18, v0
	v_mov_b32_e32 v19, v0
	v_mov_b32_e32 v20, v0
	v_mov_b32_e32 v21, v0
	v_mov_b32_e32 v22, v0
	v_mov_b32_e32 v23, v0
	v_mov_b32_e32 v32, v0
	v_mov_b32_e32 v33, v0
	v_mov_b32_e32 v34, v0
	v_mov_b32_e32 v35, v0
	v_mov_b32_e32 v36, v0
	v_mov_b32_e32 v37, v0
	v_mov_b32_e32 v38, v0
	v_mov_b32_e32 v39, v0
	v_mov_b32_e32 v48, v0
	v_mov_b32_e32 v49, v0
	v_mov_b32_e32 v50, v0
	v_mov_b32_e32 v51, v0
	v_mov_b32_e32 v52, v0
	v_mov_b32_e32 v53, v0
	v_mov_b32_e32 v54, v0
	v_mov_b32_e32 v55, v0
	v_mov_b32_e32 v8, v0
	v_mov_b32_e32 v9, v0
	v_mov_b32_e32 v10, v0
	v_mov_b32_e32 v11, v0
	v_mov_b32_e32 v12, v0
	v_mov_b32_e32 v13, v0
	v_mov_b32_e32 v14, v0
	v_mov_b32_e32 v15, v0
	v_mov_b32_e32 v24, v0
	v_mov_b32_e32 v25, v0
	v_mov_b32_e32 v26, v0
	v_mov_b32_e32 v27, v0
	v_mov_b32_e32 v28, v0
	v_mov_b32_e32 v29, v0
	v_mov_b32_e32 v30, v0
	v_mov_b32_e32 v31, v0
	v_mov_b32_e32 v40, v0
	v_mov_b32_e32 v41, v0
	v_mov_b32_e32 v42, v0
	v_mov_b32_e32 v43, v0
	v_mov_b32_e32 v44, v0
	v_mov_b32_e32 v45, v0
	v_mov_b32_e32 v46, v0
	v_mov_b32_e32 v47, v0
	v_mov_b32_e32 v56, v0
	v_mov_b32_e32 v57, v0
	v_mov_b32_e32 v58, v0
	v_mov_b32_e32 v59, v0
	v_mov_b32_e32 v60, v0
	v_mov_b32_e32 v61, v0
	v_mov_b32_e32 v62, v0
	v_mov_b32_e32 v63, v0
	v_mov_b32_e32 v64, v0
	v_mov_b32_e32 v65, v0
	v_mov_b32_e32 v66, v0
	v_mov_b32_e32 v67, v0
	v_mov_b32_e32 v68, v0
	v_mov_b32_e32 v69, v0
	v_mov_b32_e32 v70, v0
	v_mov_b32_e32 v71, v0
	v_mov_b32_e32 v80, v0
	v_mov_b32_e32 v81, v0
	v_mov_b32_e32 v82, v0
	v_mov_b32_e32 v83, v0
	v_mov_b32_e32 v84, v0
	v_mov_b32_e32 v85, v0
	v_mov_b32_e32 v86, v0
	v_mov_b32_e32 v87, v0
	v_mov_b32_e32 v96, v0
	v_mov_b32_e32 v97, v0
	v_mov_b32_e32 v98, v0
	v_mov_b32_e32 v99, v0
	v_mov_b32_e32 v100, v0
	v_mov_b32_e32 v101, v0
	v_mov_b32_e32 v102, v0
	v_mov_b32_e32 v103, v0
	v_mov_b32_e32 v112, v0
	v_mov_b32_e32 v113, v0
	v_mov_b32_e32 v114, v0
	v_mov_b32_e32 v115, v0
	v_mov_b32_e32 v116, v0
	v_mov_b32_e32 v117, v0
	v_mov_b32_e32 v118, v0
	v_mov_b32_e32 v119, v0
	v_mov_b32_e32 v72, v0
	v_mov_b32_e32 v73, v0
	v_mov_b32_e32 v74, v0
	v_mov_b32_e32 v75, v0
	v_mov_b32_e32 v76, v0
	v_mov_b32_e32 v77, v0
	v_mov_b32_e32 v78, v0
	v_mov_b32_e32 v79, v0
	v_mov_b32_e32 v88, v0
	v_mov_b32_e32 v89, v0
	v_mov_b32_e32 v90, v0
	v_mov_b32_e32 v91, v0
	v_mov_b32_e32 v92, v0
	v_mov_b32_e32 v93, v0
	v_mov_b32_e32 v94, v0
	v_mov_b32_e32 v95, v0
	v_mov_b32_e32 v104, v0
	v_mov_b32_e32 v105, v0
	v_mov_b32_e32 v106, v0
	v_mov_b32_e32 v107, v0
	v_mov_b32_e32 v108, v0
	v_mov_b32_e32 v109, v0
	v_mov_b32_e32 v110, v0
	v_mov_b32_e32 v111, v0
	v_mov_b32_e32 v120, v0
	v_mov_b32_e32 v121, v0
	v_mov_b32_e32 v122, v0
	v_mov_b32_e32 v123, v0
	v_mov_b32_e32 v124, v0
	v_mov_b32_e32 v125, v0
	v_mov_b32_e32 v126, v0
	v_mov_b32_e32 v127, v0
	.p2align 6

.LBB0_590:
	v_mov_b32_e32 v123, 0
	s_andn2_b64 vcc, exec, s[16:17]
	v_mov_b32_e32 v122, v123
	v_mov_b32_e32 v121, v123
	v_mov_b32_e32 v120, v123
	v_mov_b32_e32 v127, v123
	v_mov_b32_e32 v126, v123
	v_mov_b32_e32 v125, v123
	v_mov_b32_e32 v124, v123
	v_mov_b32_e32 v111, v123
	v_mov_b32_e32 v110, v123
	v_mov_b32_e32 v109, v123
	v_mov_b32_e32 v108, v123
	v_mov_b32_e32 v107, v123
	v_mov_b32_e32 v106, v123
	v_mov_b32_e32 v105, v123
	v_mov_b32_e32 v104, v123
	v_mov_b32_e32 v95, v123
	v_mov_b32_e32 v94, v123
	v_mov_b32_e32 v93, v123
	v_mov_b32_e32 v92, v123
	v_mov_b32_e32 v91, v123
	v_mov_b32_e32 v90, v123
	v_mov_b32_e32 v89, v123
	v_mov_b32_e32 v88, v123
	v_mov_b32_e32 v79, v123
	v_mov_b32_e32 v78, v123
	v_mov_b32_e32 v77, v123
	v_mov_b32_e32 v76, v123
	v_mov_b32_e32 v75, v123
	v_mov_b32_e32 v74, v123
	v_mov_b32_e32 v73, v123
	v_mov_b32_e32 v72, v123
	v_mov_b32_e32 v119, v123
	v_mov_b32_e32 v118, v123
	v_mov_b32_e32 v117, v123
	v_mov_b32_e32 v116, v123
	v_mov_b32_e32 v115, v123
	v_mov_b32_e32 v114, v123
	v_mov_b32_e32 v113, v123
	v_mov_b32_e32 v112, v123
	v_mov_b32_e32 v103, v123
	v_mov_b32_e32 v102, v123
	v_mov_b32_e32 v101, v123
	v_mov_b32_e32 v100, v123
	v_mov_b32_e32 v99, v123
	v_mov_b32_e32 v98, v123
	v_mov_b32_e32 v97, v123
	v_mov_b32_e32 v96, v123
	v_mov_b32_e32 v87, v123
	v_mov_b32_e32 v86, v123
	v_mov_b32_e32 v85, v123
	v_mov_b32_e32 v84, v123
	v_mov_b32_e32 v83, v123
	v_mov_b32_e32 v82, v123
	v_mov_b32_e32 v81, v123
	v_mov_b32_e32 v80, v123
	v_mov_b32_e32 v71, v123
	v_mov_b32_e32 v70, v123
	v_mov_b32_e32 v69, v123
	v_mov_b32_e32 v68, v123
	v_mov_b32_e32 v67, v123
	v_mov_b32_e32 v66, v123
	v_mov_b32_e32 v65, v123
	v_mov_b32_e32 v64, v123
	v_mov_b32_e32 v63, v123
	v_mov_b32_e32 v62, v123
	v_mov_b32_e32 v61, v123
	v_mov_b32_e32 v60, v123
	v_mov_b32_e32 v59, v123
	v_mov_b32_e32 v58, v123
	v_mov_b32_e32 v57, v123
	v_mov_b32_e32 v56, v123
	v_mov_b32_e32 v47, v123
	v_mov_b32_e32 v46, v123
	v_mov_b32_e32 v45, v123
	v_mov_b32_e32 v44, v123
	v_mov_b32_e32 v43, v123
	v_mov_b32_e32 v42, v123
	v_mov_b32_e32 v41, v123
	v_mov_b32_e32 v40, v123
	v_mov_b32_e32 v31, v123
	v_mov_b32_e32 v30, v123
	v_mov_b32_e32 v29, v123
	v_mov_b32_e32 v28, v123
	v_mov_b32_e32 v27, v123
	v_mov_b32_e32 v26, v123
	v_mov_b32_e32 v25, v123
	v_mov_b32_e32 v24, v123
	v_mov_b32_e32 v15, v123
	v_mov_b32_e32 v14, v123
	v_mov_b32_e32 v13, v123
	v_mov_b32_e32 v12, v123
	v_mov_b32_e32 v11, v123
	v_mov_b32_e32 v10, v123
	v_mov_b32_e32 v9, v123
	v_mov_b32_e32 v8, v123
	v_mov_b32_e32 v55, v123
	v_mov_b32_e32 v54, v123
	v_mov_b32_e32 v53, v123
	v_mov_b32_e32 v52, v123
	v_mov_b32_e32 v51, v123
	v_mov_b32_e32 v50, v123
	v_mov_b32_e32 v49, v123
	v_mov_b32_e32 v48, v123
	v_mov_b32_e32 v39, v123
	v_mov_b32_e32 v38, v123
	v_mov_b32_e32 v37, v123
	v_mov_b32_e32 v36, v123
	v_mov_b32_e32 v35, v123
	v_mov_b32_e32 v34, v123
	v_mov_b32_e32 v33, v123
	v_mov_b32_e32 v32, v123
	v_mov_b32_e32 v23, v123
	v_mov_b32_e32 v22, v123
	v_mov_b32_e32 v21, v123
	v_mov_b32_e32 v20, v123
	v_mov_b32_e32 v19, v123
	v_mov_b32_e32 v18, v123
	v_mov_b32_e32 v17, v123
	v_mov_b32_e32 v16, v123
	v_mov_b32_e32 v7, v123
	v_mov_b32_e32 v6, v123
	v_mov_b32_e32 v5, v123
	v_mov_b32_e32 v4, v123
	v_mov_b32_e32 v3, v123
	v_mov_b32_e32 v2, v123
	v_mov_b32_e32 v1, v123
	v_mov_b32_e32 v0, v123
	s_cbranch_vccnz .LBB0_593
	s_add_u32 s30, s30, 0x80
	s_addc_u32 s31, s31, 0
	s_add_u32 s62, s34, 0x100
	v_mov_b32_e32 v0, 0
	s_addc_u32 s63, s35, 0
	s_mov_b32 s34, 0
	v_mov_b32_e32 v1, v0
	v_mov_b32_e32 v2, v0
	v_mov_b32_e32 v3, v0
	v_mov_b32_e32 v4, v0
	v_mov_b32_e32 v5, v0
	v_mov_b32_e32 v6, v0
	v_mov_b32_e32 v7, v0
	v_mov_b32_e32 v16, v0
	v_mov_b32_e32 v17, v0
	v_mov_b32_e32 v18, v0
	v_mov_b32_e32 v19, v0
	v_mov_b32_e32 v20, v0
	v_mov_b32_e32 v21, v0
	v_mov_b32_e32 v22, v0
	v_mov_b32_e32 v23, v0
	v_mov_b32_e32 v32, v0
	v_mov_b32_e32 v33, v0
	v_mov_b32_e32 v34, v0
	v_mov_b32_e32 v35, v0
	v_mov_b32_e32 v36, v0
	v_mov_b32_e32 v37, v0
	v_mov_b32_e32 v38, v0
	v_mov_b32_e32 v39, v0
	v_mov_b32_e32 v48, v0
	v_mov_b32_e32 v49, v0
	v_mov_b32_e32 v50, v0
	v_mov_b32_e32 v51, v0
	v_mov_b32_e32 v52, v0
	v_mov_b32_e32 v53, v0
	v_mov_b32_e32 v54, v0
	v_mov_b32_e32 v55, v0
	v_mov_b32_e32 v8, v0
	v_mov_b32_e32 v9, v0
	v_mov_b32_e32 v10, v0
	v_mov_b32_e32 v11, v0
	v_mov_b32_e32 v12, v0
	v_mov_b32_e32 v13, v0
	v_mov_b32_e32 v14, v0
	v_mov_b32_e32 v15, v0
	v_mov_b32_e32 v24, v0
	v_mov_b32_e32 v25, v0
	v_mov_b32_e32 v26, v0
	v_mov_b32_e32 v27, v0
	v_mov_b32_e32 v28, v0
	v_mov_b32_e32 v29, v0
	v_mov_b32_e32 v30, v0
	v_mov_b32_e32 v31, v0
	v_mov_b32_e32 v40, v0
	v_mov_b32_e32 v41, v0
	v_mov_b32_e32 v42, v0
	v_mov_b32_e32 v43, v0
	v_mov_b32_e32 v44, v0
	v_mov_b32_e32 v45, v0
	v_mov_b32_e32 v46, v0
	v_mov_b32_e32 v47, v0
	v_mov_b32_e32 v56, v0
	v_mov_b32_e32 v57, v0
	v_mov_b32_e32 v58, v0
	v_mov_b32_e32 v59, v0
	v_mov_b32_e32 v60, v0
	v_mov_b32_e32 v61, v0
	v_mov_b32_e32 v62, v0
	v_mov_b32_e32 v63, v0
	v_mov_b32_e32 v64, v0
	v_mov_b32_e32 v65, v0
	v_mov_b32_e32 v66, v0
	v_mov_b32_e32 v67, v0
	v_mov_b32_e32 v68, v0
	v_mov_b32_e32 v69, v0
	v_mov_b32_e32 v70, v0
	v_mov_b32_e32 v71, v0
	v_mov_b32_e32 v80, v0
	v_mov_b32_e32 v81, v0
	v_mov_b32_e32 v82, v0
	v_mov_b32_e32 v83, v0
	v_mov_b32_e32 v84, v0
	v_mov_b32_e32 v85, v0
	v_mov_b32_e32 v86, v0
	v_mov_b32_e32 v87, v0
	v_mov_b32_e32 v96, v0
	v_mov_b32_e32 v97, v0
	v_mov_b32_e32 v98, v0
	v_mov_b32_e32 v99, v0
	v_mov_b32_e32 v100, v0
	v_mov_b32_e32 v101, v0
	v_mov_b32_e32 v102, v0
	v_mov_b32_e32 v103, v0
	v_mov_b32_e32 v112, v0
	v_mov_b32_e32 v113, v0
	v_mov_b32_e32 v114, v0
	v_mov_b32_e32 v115, v0
	v_mov_b32_e32 v116, v0
	v_mov_b32_e32 v117, v0
	v_mov_b32_e32 v118, v0
	v_mov_b32_e32 v119, v0
	v_mov_b32_e32 v72, v0
	v_mov_b32_e32 v73, v0
	v_mov_b32_e32 v74, v0
	v_mov_b32_e32 v75, v0
	v_mov_b32_e32 v76, v0
	v_mov_b32_e32 v77, v0
	v_mov_b32_e32 v78, v0
	v_mov_b32_e32 v79, v0
	v_mov_b32_e32 v88, v0
	v_mov_b32_e32 v89, v0
	v_mov_b32_e32 v90, v0
	v_mov_b32_e32 v91, v0
	v_mov_b32_e32 v92, v0
	v_mov_b32_e32 v93, v0
	v_mov_b32_e32 v94, v0
	v_mov_b32_e32 v95, v0
	v_mov_b32_e32 v104, v0
	v_mov_b32_e32 v105, v0
	v_mov_b32_e32 v106, v0
	v_mov_b32_e32 v107, v0
	v_mov_b32_e32 v108, v0
	v_mov_b32_e32 v109, v0
	v_mov_b32_e32 v110, v0
	v_mov_b32_e32 v111, v0
	v_mov_b32_e32 v124, v0
	v_mov_b32_e32 v125, v0
	v_mov_b32_e32 v126, v0
	v_mov_b32_e32 v127, v0
	v_mov_b32_e32 v120, v0
	v_mov_b32_e32 v121, v0
	v_mov_b32_e32 v122, v0
	v_mov_b32_e32 v123, v0
	.p2align 6

.LBB0_761:
	v_mov_b32_e32 v123, 0
	s_andn2_b64 vcc, exec, s[18:19]
	v_mov_b32_e32 v122, v123
	v_mov_b32_e32 v121, v123
	v_mov_b32_e32 v120, v123
	v_mov_b32_e32 v127, v123
	v_mov_b32_e32 v126, v123
	v_mov_b32_e32 v125, v123
	v_mov_b32_e32 v124, v123
	v_mov_b32_e32 v111, v123
	v_mov_b32_e32 v110, v123
	v_mov_b32_e32 v109, v123
	v_mov_b32_e32 v108, v123
	v_mov_b32_e32 v107, v123
	v_mov_b32_e32 v106, v123
	v_mov_b32_e32 v105, v123
	v_mov_b32_e32 v104, v123
	v_mov_b32_e32 v95, v123
	v_mov_b32_e32 v94, v123
	v_mov_b32_e32 v93, v123
	v_mov_b32_e32 v92, v123
	v_mov_b32_e32 v91, v123
	v_mov_b32_e32 v90, v123
	v_mov_b32_e32 v89, v123
	v_mov_b32_e32 v88, v123
	v_mov_b32_e32 v79, v123
	v_mov_b32_e32 v78, v123
	v_mov_b32_e32 v77, v123
	v_mov_b32_e32 v76, v123
	v_mov_b32_e32 v75, v123
	v_mov_b32_e32 v74, v123
	v_mov_b32_e32 v73, v123
	v_mov_b32_e32 v72, v123
	v_mov_b32_e32 v119, v123
	v_mov_b32_e32 v118, v123
	v_mov_b32_e32 v117, v123
	v_mov_b32_e32 v116, v123
	v_mov_b32_e32 v115, v123
	v_mov_b32_e32 v114, v123
	v_mov_b32_e32 v113, v123
	v_mov_b32_e32 v112, v123
	v_mov_b32_e32 v103, v123
	v_mov_b32_e32 v102, v123
	v_mov_b32_e32 v101, v123
	v_mov_b32_e32 v100, v123
	v_mov_b32_e32 v99, v123
	v_mov_b32_e32 v98, v123
	v_mov_b32_e32 v97, v123
	v_mov_b32_e32 v96, v123
	v_mov_b32_e32 v87, v123
	v_mov_b32_e32 v86, v123
	v_mov_b32_e32 v85, v123
	v_mov_b32_e32 v84, v123
	v_mov_b32_e32 v83, v123
	v_mov_b32_e32 v82, v123
	v_mov_b32_e32 v81, v123
	v_mov_b32_e32 v80, v123
	v_mov_b32_e32 v71, v123
	v_mov_b32_e32 v70, v123
	v_mov_b32_e32 v69, v123
	v_mov_b32_e32 v68, v123
	v_mov_b32_e32 v67, v123
	v_mov_b32_e32 v66, v123
	v_mov_b32_e32 v65, v123
	v_mov_b32_e32 v64, v123
	v_mov_b32_e32 v63, v123
	v_mov_b32_e32 v62, v123
	v_mov_b32_e32 v61, v123
	v_mov_b32_e32 v60, v123
	v_mov_b32_e32 v59, v123
	v_mov_b32_e32 v58, v123
	v_mov_b32_e32 v57, v123
	v_mov_b32_e32 v56, v123
	v_mov_b32_e32 v47, v123
	v_mov_b32_e32 v46, v123
	v_mov_b32_e32 v45, v123
	v_mov_b32_e32 v44, v123
	v_mov_b32_e32 v43, v123
	v_mov_b32_e32 v42, v123
	v_mov_b32_e32 v41, v123
	v_mov_b32_e32 v40, v123
	v_mov_b32_e32 v31, v123
	v_mov_b32_e32 v30, v123
	v_mov_b32_e32 v29, v123
	v_mov_b32_e32 v28, v123
	v_mov_b32_e32 v27, v123
	v_mov_b32_e32 v26, v123
	v_mov_b32_e32 v25, v123
	v_mov_b32_e32 v24, v123
	v_mov_b32_e32 v15, v123
	v_mov_b32_e32 v14, v123
	v_mov_b32_e32 v13, v123
	v_mov_b32_e32 v12, v123
	v_mov_b32_e32 v11, v123
	v_mov_b32_e32 v10, v123
	v_mov_b32_e32 v9, v123
	v_mov_b32_e32 v8, v123
	v_mov_b32_e32 v55, v123
	v_mov_b32_e32 v54, v123
	v_mov_b32_e32 v53, v123
	v_mov_b32_e32 v52, v123
	v_mov_b32_e32 v51, v123
	v_mov_b32_e32 v50, v123
	v_mov_b32_e32 v49, v123
	v_mov_b32_e32 v48, v123
	v_mov_b32_e32 v39, v123
	v_mov_b32_e32 v38, v123
	v_mov_b32_e32 v37, v123
	v_mov_b32_e32 v36, v123
	v_mov_b32_e32 v35, v123
	v_mov_b32_e32 v34, v123
	v_mov_b32_e32 v33, v123
	v_mov_b32_e32 v32, v123
	v_mov_b32_e32 v23, v123
	v_mov_b32_e32 v22, v123
	v_mov_b32_e32 v21, v123
	v_mov_b32_e32 v20, v123
	v_mov_b32_e32 v19, v123
	v_mov_b32_e32 v18, v123
	v_mov_b32_e32 v17, v123
	v_mov_b32_e32 v16, v123
	v_mov_b32_e32 v7, v123
	v_mov_b32_e32 v6, v123
	v_mov_b32_e32 v5, v123
	v_mov_b32_e32 v4, v123
	v_mov_b32_e32 v3, v123
	v_mov_b32_e32 v2, v123
	v_mov_b32_e32 v1, v123
	v_mov_b32_e32 v0, v123
	s_cbranch_vccnz .LBB0_764
	s_add_u32 s24, s24, 0x80
	s_addc_u32 s25, s25, 0
	s_add_u32 s52, s26, 0x100
	v_mov_b32_e32 v0, 0
	s_addc_u32 s53, s27, 0
	s_mov_b32 s26, 0
	v_mov_b32_e32 v1, v0
	v_mov_b32_e32 v2, v0
	v_mov_b32_e32 v3, v0
	v_mov_b32_e32 v4, v0
	v_mov_b32_e32 v5, v0
	v_mov_b32_e32 v6, v0
	v_mov_b32_e32 v7, v0
	v_mov_b32_e32 v16, v0
	v_mov_b32_e32 v17, v0
	v_mov_b32_e32 v18, v0
	v_mov_b32_e32 v19, v0
	v_mov_b32_e32 v20, v0
	v_mov_b32_e32 v21, v0
	v_mov_b32_e32 v22, v0
	v_mov_b32_e32 v23, v0
	v_mov_b32_e32 v32, v0
	v_mov_b32_e32 v33, v0
	v_mov_b32_e32 v34, v0
	v_mov_b32_e32 v35, v0
	v_mov_b32_e32 v36, v0
	v_mov_b32_e32 v37, v0
	v_mov_b32_e32 v38, v0
	v_mov_b32_e32 v39, v0
	v_mov_b32_e32 v48, v0
	v_mov_b32_e32 v49, v0
	v_mov_b32_e32 v50, v0
	v_mov_b32_e32 v51, v0
	v_mov_b32_e32 v52, v0
	v_mov_b32_e32 v53, v0
	v_mov_b32_e32 v54, v0
	v_mov_b32_e32 v55, v0
	v_mov_b32_e32 v8, v0
	v_mov_b32_e32 v9, v0
	v_mov_b32_e32 v10, v0
	v_mov_b32_e32 v11, v0
	v_mov_b32_e32 v12, v0
	v_mov_b32_e32 v13, v0
	v_mov_b32_e32 v14, v0
	v_mov_b32_e32 v15, v0
	v_mov_b32_e32 v24, v0
	v_mov_b32_e32 v25, v0
	v_mov_b32_e32 v26, v0
	v_mov_b32_e32 v27, v0
	v_mov_b32_e32 v28, v0
	v_mov_b32_e32 v29, v0
	v_mov_b32_e32 v30, v0
	v_mov_b32_e32 v31, v0
	v_mov_b32_e32 v40, v0
	v_mov_b32_e32 v41, v0
	v_mov_b32_e32 v42, v0
	v_mov_b32_e32 v43, v0
	v_mov_b32_e32 v44, v0
	v_mov_b32_e32 v45, v0
	v_mov_b32_e32 v46, v0
	v_mov_b32_e32 v47, v0
	v_mov_b32_e32 v56, v0
	v_mov_b32_e32 v57, v0
	v_mov_b32_e32 v58, v0
	v_mov_b32_e32 v59, v0
	v_mov_b32_e32 v60, v0
	v_mov_b32_e32 v61, v0
	v_mov_b32_e32 v62, v0
	v_mov_b32_e32 v63, v0
	v_mov_b32_e32 v64, v0
	v_mov_b32_e32 v65, v0
	v_mov_b32_e32 v66, v0
	v_mov_b32_e32 v67, v0
	v_mov_b32_e32 v68, v0
	v_mov_b32_e32 v69, v0
	v_mov_b32_e32 v70, v0
	v_mov_b32_e32 v71, v0
	v_mov_b32_e32 v80, v0
	v_mov_b32_e32 v81, v0
	v_mov_b32_e32 v82, v0
	v_mov_b32_e32 v83, v0
	v_mov_b32_e32 v84, v0
	v_mov_b32_e32 v85, v0
	v_mov_b32_e32 v86, v0
	v_mov_b32_e32 v87, v0
	v_mov_b32_e32 v96, v0
	v_mov_b32_e32 v97, v0
	v_mov_b32_e32 v98, v0
	v_mov_b32_e32 v99, v0
	v_mov_b32_e32 v100, v0
	v_mov_b32_e32 v101, v0
	v_mov_b32_e32 v102, v0
	v_mov_b32_e32 v103, v0
	v_mov_b32_e32 v112, v0
	v_mov_b32_e32 v113, v0
	v_mov_b32_e32 v114, v0
	v_mov_b32_e32 v115, v0
	v_mov_b32_e32 v116, v0
	v_mov_b32_e32 v117, v0
	v_mov_b32_e32 v118, v0
	v_mov_b32_e32 v119, v0
	v_mov_b32_e32 v72, v0
	v_mov_b32_e32 v73, v0
	v_mov_b32_e32 v74, v0
	v_mov_b32_e32 v75, v0
	v_mov_b32_e32 v76, v0
	v_mov_b32_e32 v77, v0
	v_mov_b32_e32 v78, v0
	v_mov_b32_e32 v79, v0
	v_mov_b32_e32 v88, v0
	v_mov_b32_e32 v89, v0
	v_mov_b32_e32 v90, v0
	v_mov_b32_e32 v91, v0
	v_mov_b32_e32 v92, v0
	v_mov_b32_e32 v93, v0
	v_mov_b32_e32 v94, v0
	v_mov_b32_e32 v95, v0
	v_mov_b32_e32 v104, v0
	v_mov_b32_e32 v105, v0
	v_mov_b32_e32 v106, v0
	v_mov_b32_e32 v107, v0
	v_mov_b32_e32 v108, v0
	v_mov_b32_e32 v109, v0
	v_mov_b32_e32 v110, v0
	v_mov_b32_e32 v111, v0
	v_mov_b32_e32 v124, v0
	v_mov_b32_e32 v125, v0
	v_mov_b32_e32 v126, v0
	v_mov_b32_e32 v127, v0
	v_mov_b32_e32 v120, v0
	v_mov_b32_e32 v121, v0
	v_mov_b32_e32 v122, v0
	v_mov_b32_e32 v123, v0
	.p2align 6

.LBB0_847:
	v_mov_b32_e32 v139, 0
	s_andn2_b64 vcc, exec, s[20:21]
	v_mov_b32_e32 v138, v139
	v_mov_b32_e32 v137, v139
	v_mov_b32_e32 v136, v139
	v_mov_b32_e32 v143, v139
	v_mov_b32_e32 v142, v139
	v_mov_b32_e32 v141, v139
	v_mov_b32_e32 v140, v139
	v_mov_b32_e32 v111, v139
	v_mov_b32_e32 v110, v139
	v_mov_b32_e32 v109, v139
	v_mov_b32_e32 v108, v139
	v_mov_b32_e32 v107, v139
	v_mov_b32_e32 v106, v139
	v_mov_b32_e32 v105, v139
	v_mov_b32_e32 v104, v139
	v_mov_b32_e32 v95, v139
	v_mov_b32_e32 v94, v139
	v_mov_b32_e32 v93, v139
	v_mov_b32_e32 v92, v139
	v_mov_b32_e32 v91, v139
	v_mov_b32_e32 v90, v139
	v_mov_b32_e32 v89, v139
	v_mov_b32_e32 v88, v139
	v_mov_b32_e32 v79, v139
	v_mov_b32_e32 v78, v139
	v_mov_b32_e32 v77, v139
	v_mov_b32_e32 v76, v139
	v_mov_b32_e32 v75, v139
	v_mov_b32_e32 v74, v139
	v_mov_b32_e32 v73, v139
	v_mov_b32_e32 v72, v139
	v_mov_b32_e32 v135, v139
	v_mov_b32_e32 v134, v139
	v_mov_b32_e32 v133, v139
	v_mov_b32_e32 v132, v139
	v_mov_b32_e32 v127, v139
	v_mov_b32_e32 v126, v139
	v_mov_b32_e32 v125, v139
	v_mov_b32_e32 v124, v139
	v_mov_b32_e32 v103, v139
	v_mov_b32_e32 v102, v139
	v_mov_b32_e32 v101, v139
	v_mov_b32_e32 v100, v139
	v_mov_b32_e32 v99, v139
	v_mov_b32_e32 v98, v139
	v_mov_b32_e32 v97, v139
	v_mov_b32_e32 v96, v139
	v_mov_b32_e32 v87, v139
	v_mov_b32_e32 v86, v139
	v_mov_b32_e32 v85, v139
	v_mov_b32_e32 v84, v139
	v_mov_b32_e32 v83, v139
	v_mov_b32_e32 v82, v139
	v_mov_b32_e32 v81, v139
	v_mov_b32_e32 v80, v139
	v_mov_b32_e32 v71, v139
	v_mov_b32_e32 v70, v139
	v_mov_b32_e32 v69, v139
	v_mov_b32_e32 v68, v139
	v_mov_b32_e32 v67, v139
	v_mov_b32_e32 v66, v139
	v_mov_b32_e32 v65, v139
	v_mov_b32_e32 v64, v139
	v_mov_b32_e32 v63, v139
	v_mov_b32_e32 v62, v139
	v_mov_b32_e32 v61, v139
	v_mov_b32_e32 v60, v139
	v_mov_b32_e32 v59, v139
	v_mov_b32_e32 v58, v139
	v_mov_b32_e32 v57, v139
	v_mov_b32_e32 v56, v139
	v_mov_b32_e32 v47, v139
	v_mov_b32_e32 v46, v139
	v_mov_b32_e32 v45, v139
	v_mov_b32_e32 v44, v139
	v_mov_b32_e32 v43, v139
	v_mov_b32_e32 v42, v139
	v_mov_b32_e32 v41, v139
	v_mov_b32_e32 v40, v139
	v_mov_b32_e32 v31, v139
	v_mov_b32_e32 v30, v139
	v_mov_b32_e32 v29, v139
	v_mov_b32_e32 v28, v139
	v_mov_b32_e32 v27, v139
	v_mov_b32_e32 v26, v139
	v_mov_b32_e32 v25, v139
	v_mov_b32_e32 v24, v139
	v_mov_b32_e32 v15, v139
	v_mov_b32_e32 v14, v139
	v_mov_b32_e32 v13, v139
	v_mov_b32_e32 v12, v139
	v_mov_b32_e32 v11, v139
	v_mov_b32_e32 v10, v139
	v_mov_b32_e32 v9, v139
	v_mov_b32_e32 v8, v139
	v_mov_b32_e32 v55, v139
	v_mov_b32_e32 v54, v139
	v_mov_b32_e32 v53, v139
	v_mov_b32_e32 v52, v139
	v_mov_b32_e32 v51, v139
	v_mov_b32_e32 v50, v139
	v_mov_b32_e32 v49, v139
	v_mov_b32_e32 v48, v139
	v_mov_b32_e32 v39, v139
	v_mov_b32_e32 v38, v139
	v_mov_b32_e32 v37, v139
	v_mov_b32_e32 v36, v139
	v_mov_b32_e32 v35, v139
	v_mov_b32_e32 v34, v139
	v_mov_b32_e32 v33, v139
	v_mov_b32_e32 v32, v139
	v_mov_b32_e32 v23, v139
	v_mov_b32_e32 v22, v139
	v_mov_b32_e32 v21, v139
	v_mov_b32_e32 v20, v139
	v_mov_b32_e32 v19, v139
	v_mov_b32_e32 v18, v139
	v_mov_b32_e32 v17, v139
	v_mov_b32_e32 v16, v139
	v_mov_b32_e32 v7, v139
	v_mov_b32_e32 v6, v139
	v_mov_b32_e32 v5, v139
	v_mov_b32_e32 v4, v139
	v_mov_b32_e32 v3, v139
	v_mov_b32_e32 v2, v139
	s_waitcnt lgkmcnt(0)
	v_mov_b32_e32 v1, v139
	v_mov_b32_e32 v0, v139
	s_cbranch_vccnz .LBB0_850
	s_add_u32 s28, s28, 0x80
	s_addc_u32 s29, s29, 0
	s_add_u32 s60, s30, 0x100
	v_mov_b32_e32 v0, 0
	s_addc_u32 s61, s31, 0
	s_mov_b32 s30, 0
	v_mov_b32_e32 v1, v0
	v_mov_b32_e32 v2, v0
	v_mov_b32_e32 v3, v0
	v_mov_b32_e32 v4, v0
	v_mov_b32_e32 v5, v0
	v_mov_b32_e32 v6, v0
	v_mov_b32_e32 v7, v0
	v_mov_b32_e32 v16, v0
	v_mov_b32_e32 v17, v0
	v_mov_b32_e32 v18, v0
	v_mov_b32_e32 v19, v0
	v_mov_b32_e32 v20, v0
	v_mov_b32_e32 v21, v0
	v_mov_b32_e32 v22, v0
	v_mov_b32_e32 v23, v0
	v_mov_b32_e32 v32, v0
	v_mov_b32_e32 v33, v0
	v_mov_b32_e32 v34, v0
	v_mov_b32_e32 v35, v0
	v_mov_b32_e32 v36, v0
	v_mov_b32_e32 v37, v0
	v_mov_b32_e32 v38, v0
	v_mov_b32_e32 v39, v0
	v_mov_b32_e32 v48, v0
	v_mov_b32_e32 v49, v0
	v_mov_b32_e32 v50, v0
	v_mov_b32_e32 v51, v0
	v_mov_b32_e32 v52, v0
	v_mov_b32_e32 v53, v0
	v_mov_b32_e32 v54, v0
	v_mov_b32_e32 v55, v0
	v_mov_b32_e32 v8, v0
	v_mov_b32_e32 v9, v0
	v_mov_b32_e32 v10, v0
	v_mov_b32_e32 v11, v0
	v_mov_b32_e32 v12, v0
	v_mov_b32_e32 v13, v0
	v_mov_b32_e32 v14, v0
	v_mov_b32_e32 v15, v0
	v_mov_b32_e32 v24, v0
	v_mov_b32_e32 v25, v0
	v_mov_b32_e32 v26, v0
	v_mov_b32_e32 v27, v0
	v_mov_b32_e32 v28, v0
	v_mov_b32_e32 v29, v0
	v_mov_b32_e32 v30, v0
	v_mov_b32_e32 v31, v0
	v_mov_b32_e32 v40, v0
	v_mov_b32_e32 v41, v0
	v_mov_b32_e32 v42, v0
	v_mov_b32_e32 v43, v0
	v_mov_b32_e32 v44, v0
	v_mov_b32_e32 v45, v0
	v_mov_b32_e32 v46, v0
	v_mov_b32_e32 v47, v0
	v_mov_b32_e32 v56, v0
	v_mov_b32_e32 v57, v0
	v_mov_b32_e32 v58, v0
	v_mov_b32_e32 v59, v0
	v_mov_b32_e32 v60, v0
	v_mov_b32_e32 v61, v0
	v_mov_b32_e32 v62, v0
	v_mov_b32_e32 v63, v0
	v_mov_b32_e32 v64, v0
	v_mov_b32_e32 v65, v0
	v_mov_b32_e32 v66, v0
	v_mov_b32_e32 v67, v0
	v_mov_b32_e32 v68, v0
	v_mov_b32_e32 v69, v0
	v_mov_b32_e32 v70, v0
	v_mov_b32_e32 v71, v0
	v_mov_b32_e32 v80, v0
	v_mov_b32_e32 v81, v0
	v_mov_b32_e32 v82, v0
	v_mov_b32_e32 v83, v0
	v_mov_b32_e32 v84, v0
	v_mov_b32_e32 v85, v0
	v_mov_b32_e32 v86, v0
	v_mov_b32_e32 v87, v0
	v_mov_b32_e32 v96, v0
	v_mov_b32_e32 v97, v0
	v_mov_b32_e32 v98, v0
	v_mov_b32_e32 v99, v0
	v_mov_b32_e32 v100, v0
	v_mov_b32_e32 v101, v0
	v_mov_b32_e32 v102, v0
	v_mov_b32_e32 v103, v0
	v_mov_b32_e32 v124, v0
	v_mov_b32_e32 v125, v0
	v_mov_b32_e32 v126, v0
	v_mov_b32_e32 v127, v0
	v_mov_b32_e32 v132, v0
	v_mov_b32_e32 v133, v0
	v_mov_b32_e32 v134, v0
	v_mov_b32_e32 v135, v0
	v_mov_b32_e32 v72, v0
	v_mov_b32_e32 v73, v0
	v_mov_b32_e32 v74, v0
	v_mov_b32_e32 v75, v0
	v_mov_b32_e32 v76, v0
	v_mov_b32_e32 v77, v0
	v_mov_b32_e32 v78, v0
	v_mov_b32_e32 v79, v0
	v_mov_b32_e32 v88, v0
	v_mov_b32_e32 v89, v0
	v_mov_b32_e32 v90, v0
	v_mov_b32_e32 v91, v0
	v_mov_b32_e32 v92, v0
	v_mov_b32_e32 v93, v0
	v_mov_b32_e32 v94, v0
	v_mov_b32_e32 v95, v0
	v_mov_b32_e32 v104, v0
	v_mov_b32_e32 v105, v0
	v_mov_b32_e32 v106, v0
	v_mov_b32_e32 v107, v0
	v_mov_b32_e32 v108, v0
	v_mov_b32_e32 v109, v0
	v_mov_b32_e32 v110, v0
	v_mov_b32_e32 v111, v0
	v_mov_b32_e32 v140, v0
	v_mov_b32_e32 v141, v0
	v_mov_b32_e32 v142, v0
	v_mov_b32_e32 v143, v0
	v_mov_b32_e32 v136, v0
	v_mov_b32_e32 v137, v0
	v_mov_b32_e32 v138, v0
	v_mov_b32_e32 v139, v0
	.p2align 6

.LBB0_947:
	v_mov_b32_e32 v123, 0
	s_andn2_b64 vcc, exec, s[16:17]
	v_mov_b32_e32 v122, v123
	v_mov_b32_e32 v121, v123
	v_mov_b32_e32 v120, v123
	v_mov_b32_e32 v127, v123
	v_mov_b32_e32 v126, v123
	v_mov_b32_e32 v125, v123
	v_mov_b32_e32 v124, v123
	v_mov_b32_e32 v111, v123
	v_mov_b32_e32 v110, v123
	v_mov_b32_e32 v109, v123
	v_mov_b32_e32 v108, v123
	v_mov_b32_e32 v107, v123
	v_mov_b32_e32 v106, v123
	v_mov_b32_e32 v105, v123
	v_mov_b32_e32 v104, v123
	v_mov_b32_e32 v95, v123
	v_mov_b32_e32 v94, v123
	v_mov_b32_e32 v93, v123
	v_mov_b32_e32 v92, v123
	v_mov_b32_e32 v91, v123
	v_mov_b32_e32 v90, v123
	v_mov_b32_e32 v89, v123
	v_mov_b32_e32 v88, v123
	v_mov_b32_e32 v79, v123
	v_mov_b32_e32 v78, v123
	v_mov_b32_e32 v77, v123
	v_mov_b32_e32 v76, v123
	v_mov_b32_e32 v75, v123
	v_mov_b32_e32 v74, v123
	v_mov_b32_e32 v73, v123
	v_mov_b32_e32 v72, v123
	v_mov_b32_e32 v119, v123
	v_mov_b32_e32 v118, v123
	v_mov_b32_e32 v117, v123
	v_mov_b32_e32 v116, v123
	v_mov_b32_e32 v115, v123
	v_mov_b32_e32 v114, v123
	v_mov_b32_e32 v113, v123
	v_mov_b32_e32 v112, v123
	v_mov_b32_e32 v103, v123
	v_mov_b32_e32 v102, v123
	v_mov_b32_e32 v101, v123
	v_mov_b32_e32 v100, v123
	v_mov_b32_e32 v99, v123
	v_mov_b32_e32 v98, v123
	v_mov_b32_e32 v97, v123
	v_mov_b32_e32 v96, v123
	v_mov_b32_e32 v87, v123
	v_mov_b32_e32 v86, v123
	v_mov_b32_e32 v85, v123
	v_mov_b32_e32 v84, v123
	v_mov_b32_e32 v83, v123
	v_mov_b32_e32 v82, v123
	v_mov_b32_e32 v81, v123
	v_mov_b32_e32 v80, v123
	v_mov_b32_e32 v71, v123
	v_mov_b32_e32 v70, v123
	v_mov_b32_e32 v69, v123
	v_mov_b32_e32 v68, v123
	v_mov_b32_e32 v67, v123
	v_mov_b32_e32 v66, v123
	v_mov_b32_e32 v65, v123
	v_mov_b32_e32 v64, v123
	v_mov_b32_e32 v63, v123
	v_mov_b32_e32 v62, v123
	v_mov_b32_e32 v61, v123
	v_mov_b32_e32 v60, v123
	v_mov_b32_e32 v59, v123
	v_mov_b32_e32 v58, v123
	v_mov_b32_e32 v57, v123
	v_mov_b32_e32 v56, v123
	v_mov_b32_e32 v47, v123
	v_mov_b32_e32 v46, v123
	v_mov_b32_e32 v45, v123
	v_mov_b32_e32 v44, v123
	v_mov_b32_e32 v43, v123
	v_mov_b32_e32 v42, v123
	v_mov_b32_e32 v41, v123
	v_mov_b32_e32 v40, v123
	v_mov_b32_e32 v31, v123
	v_mov_b32_e32 v30, v123
	v_mov_b32_e32 v29, v123
	v_mov_b32_e32 v28, v123
	v_mov_b32_e32 v27, v123
	v_mov_b32_e32 v26, v123
	v_mov_b32_e32 v25, v123
	v_mov_b32_e32 v24, v123
	v_mov_b32_e32 v15, v123
	v_mov_b32_e32 v14, v123
	v_mov_b32_e32 v13, v123
	v_mov_b32_e32 v12, v123
	v_mov_b32_e32 v11, v123
	v_mov_b32_e32 v10, v123
	v_mov_b32_e32 v9, v123
	v_mov_b32_e32 v8, v123
	v_mov_b32_e32 v55, v123
	v_mov_b32_e32 v54, v123
	v_mov_b32_e32 v53, v123
	v_mov_b32_e32 v52, v123
	v_mov_b32_e32 v51, v123
	v_mov_b32_e32 v50, v123
	v_mov_b32_e32 v49, v123
	v_mov_b32_e32 v48, v123
	v_mov_b32_e32 v39, v123
	v_mov_b32_e32 v38, v123
	v_mov_b32_e32 v37, v123
	v_mov_b32_e32 v36, v123
	v_mov_b32_e32 v35, v123
	v_mov_b32_e32 v34, v123
	v_mov_b32_e32 v33, v123
	v_mov_b32_e32 v32, v123
	v_mov_b32_e32 v23, v123
	v_mov_b32_e32 v22, v123
	v_mov_b32_e32 v21, v123
	v_mov_b32_e32 v20, v123
	v_mov_b32_e32 v19, v123
	v_mov_b32_e32 v18, v123
	v_mov_b32_e32 v17, v123
	v_mov_b32_e32 v16, v123
	v_mov_b32_e32 v7, v123
	v_mov_b32_e32 v6, v123
	v_mov_b32_e32 v5, v123
	v_mov_b32_e32 v4, v123
	v_mov_b32_e32 v3, v123
	v_mov_b32_e32 v2, v123
	v_mov_b32_e32 v1, v123
	v_mov_b32_e32 v0, v123
	s_cbranch_vccnz .LBB0_950
	s_add_u32 s30, s30, 0x80
	s_addc_u32 s31, s31, 0
	s_add_u32 s66, s34, 0x100
	v_mov_b32_e32 v0, 0
	s_addc_u32 s67, s35, 0
	s_mov_b32 s34, 0
	v_mov_b32_e32 v1, v0
	v_mov_b32_e32 v2, v0
	v_mov_b32_e32 v3, v0
	v_mov_b32_e32 v4, v0
	v_mov_b32_e32 v5, v0
	v_mov_b32_e32 v6, v0
	v_mov_b32_e32 v7, v0
	v_mov_b32_e32 v16, v0
	v_mov_b32_e32 v17, v0
	v_mov_b32_e32 v18, v0
	v_mov_b32_e32 v19, v0
	v_mov_b32_e32 v20, v0
	v_mov_b32_e32 v21, v0
	v_mov_b32_e32 v22, v0
	v_mov_b32_e32 v23, v0
	v_mov_b32_e32 v32, v0
	v_mov_b32_e32 v33, v0
	v_mov_b32_e32 v34, v0
	v_mov_b32_e32 v35, v0
	v_mov_b32_e32 v36, v0
	v_mov_b32_e32 v37, v0
	v_mov_b32_e32 v38, v0
	v_mov_b32_e32 v39, v0
	v_mov_b32_e32 v48, v0
	v_mov_b32_e32 v49, v0
	v_mov_b32_e32 v50, v0
	v_mov_b32_e32 v51, v0
	v_mov_b32_e32 v52, v0
	v_mov_b32_e32 v53, v0
	v_mov_b32_e32 v54, v0
	v_mov_b32_e32 v55, v0
	v_mov_b32_e32 v8, v0
	v_mov_b32_e32 v9, v0
	v_mov_b32_e32 v10, v0
	v_mov_b32_e32 v11, v0
	v_mov_b32_e32 v12, v0
	v_mov_b32_e32 v13, v0
	v_mov_b32_e32 v14, v0
	v_mov_b32_e32 v15, v0
	v_mov_b32_e32 v24, v0
	v_mov_b32_e32 v25, v0
	v_mov_b32_e32 v26, v0
	v_mov_b32_e32 v27, v0
	v_mov_b32_e32 v28, v0
	v_mov_b32_e32 v29, v0
	v_mov_b32_e32 v30, v0
	v_mov_b32_e32 v31, v0
	v_mov_b32_e32 v40, v0
	v_mov_b32_e32 v41, v0
	v_mov_b32_e32 v42, v0
	v_mov_b32_e32 v43, v0
	v_mov_b32_e32 v44, v0
	v_mov_b32_e32 v45, v0
	v_mov_b32_e32 v46, v0
	v_mov_b32_e32 v47, v0
	v_mov_b32_e32 v56, v0
	v_mov_b32_e32 v57, v0
	v_mov_b32_e32 v58, v0
	v_mov_b32_e32 v59, v0
	v_mov_b32_e32 v60, v0
	v_mov_b32_e32 v61, v0
	v_mov_b32_e32 v62, v0
	v_mov_b32_e32 v63, v0
	v_mov_b32_e32 v64, v0
	v_mov_b32_e32 v65, v0
	v_mov_b32_e32 v66, v0
	v_mov_b32_e32 v67, v0
	v_mov_b32_e32 v68, v0
	v_mov_b32_e32 v69, v0
	v_mov_b32_e32 v70, v0
	v_mov_b32_e32 v71, v0
	v_mov_b32_e32 v80, v0
	v_mov_b32_e32 v81, v0
	v_mov_b32_e32 v82, v0
	v_mov_b32_e32 v83, v0
	v_mov_b32_e32 v84, v0
	v_mov_b32_e32 v85, v0
	v_mov_b32_e32 v86, v0
	v_mov_b32_e32 v87, v0
	v_mov_b32_e32 v96, v0
	v_mov_b32_e32 v97, v0
	v_mov_b32_e32 v98, v0
	v_mov_b32_e32 v99, v0
	v_mov_b32_e32 v100, v0
	v_mov_b32_e32 v101, v0
	v_mov_b32_e32 v102, v0
	v_mov_b32_e32 v103, v0
	v_mov_b32_e32 v112, v0
	v_mov_b32_e32 v113, v0
	v_mov_b32_e32 v114, v0
	v_mov_b32_e32 v115, v0
	v_mov_b32_e32 v116, v0
	v_mov_b32_e32 v117, v0
	v_mov_b32_e32 v118, v0
	v_mov_b32_e32 v119, v0
	v_mov_b32_e32 v72, v0
	v_mov_b32_e32 v73, v0
	v_mov_b32_e32 v74, v0
	v_mov_b32_e32 v75, v0
	v_mov_b32_e32 v76, v0
	v_mov_b32_e32 v77, v0
	v_mov_b32_e32 v78, v0
	v_mov_b32_e32 v79, v0
	v_mov_b32_e32 v88, v0
	v_mov_b32_e32 v89, v0
	v_mov_b32_e32 v90, v0
	v_mov_b32_e32 v91, v0
	v_mov_b32_e32 v92, v0
	v_mov_b32_e32 v93, v0
	v_mov_b32_e32 v94, v0
	v_mov_b32_e32 v95, v0
	v_mov_b32_e32 v104, v0
	v_mov_b32_e32 v105, v0
	v_mov_b32_e32 v106, v0
	v_mov_b32_e32 v107, v0
	v_mov_b32_e32 v108, v0
	v_mov_b32_e32 v109, v0
	v_mov_b32_e32 v110, v0
	v_mov_b32_e32 v111, v0
	v_mov_b32_e32 v124, v0
	v_mov_b32_e32 v125, v0
	v_mov_b32_e32 v126, v0
	v_mov_b32_e32 v127, v0
	v_mov_b32_e32 v120, v0
	v_mov_b32_e32 v121, v0
	v_mov_b32_e32 v122, v0
	v_mov_b32_e32 v123, v0
	.p2align 6

.LBB0_968:
	v_mov_b32_e32 v127, 0
	s_andn2_b64 vcc, exec, s[26:27]
	v_mov_b32_e32 v126, v127
	v_mov_b32_e32 v125, v127
	v_mov_b32_e32 v124, v127
	v_mov_b32_e32 v123, v127
	v_mov_b32_e32 v122, v127
	v_mov_b32_e32 v121, v127
	v_mov_b32_e32 v120, v127
	v_mov_b32_e32 v111, v127
	v_mov_b32_e32 v110, v127
	v_mov_b32_e32 v109, v127
	v_mov_b32_e32 v108, v127
	v_mov_b32_e32 v107, v127
	v_mov_b32_e32 v106, v127
	v_mov_b32_e32 v105, v127
	v_mov_b32_e32 v104, v127
	v_mov_b32_e32 v95, v127
	v_mov_b32_e32 v94, v127
	v_mov_b32_e32 v93, v127
	v_mov_b32_e32 v92, v127
	v_mov_b32_e32 v91, v127
	v_mov_b32_e32 v90, v127
	v_mov_b32_e32 v89, v127
	v_mov_b32_e32 v88, v127
	v_mov_b32_e32 v79, v127
	v_mov_b32_e32 v78, v127
	v_mov_b32_e32 v77, v127
	v_mov_b32_e32 v76, v127
	v_mov_b32_e32 v75, v127
	v_mov_b32_e32 v74, v127
	v_mov_b32_e32 v73, v127
	v_mov_b32_e32 v72, v127
	v_mov_b32_e32 v119, v127
	v_mov_b32_e32 v118, v127
	v_mov_b32_e32 v117, v127
	v_mov_b32_e32 v116, v127
	v_mov_b32_e32 v115, v127
	v_mov_b32_e32 v114, v127
	v_mov_b32_e32 v113, v127
	v_mov_b32_e32 v112, v127
	v_mov_b32_e32 v103, v127
	v_mov_b32_e32 v102, v127
	v_mov_b32_e32 v101, v127
	v_mov_b32_e32 v100, v127
	v_mov_b32_e32 v99, v127
	v_mov_b32_e32 v98, v127
	v_mov_b32_e32 v97, v127
	v_mov_b32_e32 v96, v127
	v_mov_b32_e32 v87, v127
	v_mov_b32_e32 v86, v127
	v_mov_b32_e32 v85, v127
	v_mov_b32_e32 v84, v127
	v_mov_b32_e32 v83, v127
	v_mov_b32_e32 v82, v127
	v_mov_b32_e32 v81, v127
	v_mov_b32_e32 v80, v127
	v_mov_b32_e32 v71, v127
	v_mov_b32_e32 v70, v127
	v_mov_b32_e32 v69, v127
	v_mov_b32_e32 v68, v127
	v_mov_b32_e32 v67, v127
	v_mov_b32_e32 v66, v127
	v_mov_b32_e32 v65, v127
	v_mov_b32_e32 v64, v127
	v_mov_b32_e32 v63, v127
	v_mov_b32_e32 v62, v127
	v_mov_b32_e32 v61, v127
	v_mov_b32_e32 v60, v127
	v_mov_b32_e32 v59, v127
	v_mov_b32_e32 v58, v127
	v_mov_b32_e32 v57, v127
	v_mov_b32_e32 v56, v127
	v_mov_b32_e32 v47, v127
	v_mov_b32_e32 v46, v127
	v_mov_b32_e32 v45, v127
	v_mov_b32_e32 v44, v127
	v_mov_b32_e32 v43, v127
	v_mov_b32_e32 v42, v127
	v_mov_b32_e32 v41, v127
	v_mov_b32_e32 v40, v127
	v_mov_b32_e32 v31, v127
	v_mov_b32_e32 v30, v127
	v_mov_b32_e32 v29, v127
	v_mov_b32_e32 v28, v127
	v_mov_b32_e32 v27, v127
	v_mov_b32_e32 v26, v127
	v_mov_b32_e32 v25, v127
	v_mov_b32_e32 v24, v127
	v_mov_b32_e32 v15, v127
	v_mov_b32_e32 v14, v127
	v_mov_b32_e32 v13, v127
	v_mov_b32_e32 v12, v127
	v_mov_b32_e32 v11, v127
	v_mov_b32_e32 v10, v127
	v_mov_b32_e32 v9, v127
	v_mov_b32_e32 v8, v127
	v_mov_b32_e32 v55, v127
	v_mov_b32_e32 v54, v127
	v_mov_b32_e32 v53, v127
	v_mov_b32_e32 v52, v127
	v_mov_b32_e32 v51, v127
	v_mov_b32_e32 v50, v127
	v_mov_b32_e32 v49, v127
	v_mov_b32_e32 v48, v127
	v_mov_b32_e32 v39, v127
	v_mov_b32_e32 v38, v127
	v_mov_b32_e32 v37, v127
	v_mov_b32_e32 v36, v127
	v_mov_b32_e32 v35, v127
	v_mov_b32_e32 v34, v127
	v_mov_b32_e32 v33, v127
	v_mov_b32_e32 v32, v127
	v_mov_b32_e32 v23, v127
	v_mov_b32_e32 v22, v127
	v_mov_b32_e32 v21, v127
	v_mov_b32_e32 v20, v127
	v_mov_b32_e32 v19, v127
	v_mov_b32_e32 v18, v127
	v_mov_b32_e32 v17, v127
	v_mov_b32_e32 v16, v127
	v_mov_b32_e32 v7, v127
	v_mov_b32_e32 v6, v127
	v_mov_b32_e32 v5, v127
	v_mov_b32_e32 v4, v127
	v_mov_b32_e32 v3, v127
	v_mov_b32_e32 v2, v127
	v_mov_b32_e32 v1, v127
	v_mov_b32_e32 v0, v127
	s_cbranch_vccnz .LBB0_971
	s_add_u32 s2, s6, 0x80
	s_addc_u32 s3, s7, 0
	s_add_u32 s6, s4, 0x100
	v_mov_b32_e32 v0, 0
	s_addc_u32 s7, s5, 0
	s_mov_b32 s4, 0
	v_mov_b32_e32 v1, v0
	v_mov_b32_e32 v2, v0
	v_mov_b32_e32 v3, v0
	v_mov_b32_e32 v4, v0
	v_mov_b32_e32 v5, v0
	v_mov_b32_e32 v6, v0
	v_mov_b32_e32 v7, v0
	v_mov_b32_e32 v16, v0
	v_mov_b32_e32 v17, v0
	v_mov_b32_e32 v18, v0
	v_mov_b32_e32 v19, v0
	v_mov_b32_e32 v20, v0
	v_mov_b32_e32 v21, v0
	v_mov_b32_e32 v22, v0
	v_mov_b32_e32 v23, v0
	v_mov_b32_e32 v32, v0
	v_mov_b32_e32 v33, v0
	v_mov_b32_e32 v34, v0
	v_mov_b32_e32 v35, v0
	v_mov_b32_e32 v36, v0
	v_mov_b32_e32 v37, v0
	v_mov_b32_e32 v38, v0
	v_mov_b32_e32 v39, v0
	v_mov_b32_e32 v48, v0
	v_mov_b32_e32 v49, v0
	v_mov_b32_e32 v50, v0
	v_mov_b32_e32 v51, v0
	v_mov_b32_e32 v52, v0
	v_mov_b32_e32 v53, v0
	v_mov_b32_e32 v54, v0
	v_mov_b32_e32 v55, v0
	v_mov_b32_e32 v8, v0
	v_mov_b32_e32 v9, v0
	v_mov_b32_e32 v10, v0
	v_mov_b32_e32 v11, v0
	v_mov_b32_e32 v12, v0
	v_mov_b32_e32 v13, v0
	v_mov_b32_e32 v14, v0
	v_mov_b32_e32 v15, v0
	v_mov_b32_e32 v24, v0
	v_mov_b32_e32 v25, v0
	v_mov_b32_e32 v26, v0
	v_mov_b32_e32 v27, v0
	v_mov_b32_e32 v28, v0
	v_mov_b32_e32 v29, v0
	v_mov_b32_e32 v30, v0
	v_mov_b32_e32 v31, v0
	v_mov_b32_e32 v40, v0
	v_mov_b32_e32 v41, v0
	v_mov_b32_e32 v42, v0
	v_mov_b32_e32 v43, v0
	v_mov_b32_e32 v44, v0
	v_mov_b32_e32 v45, v0
	v_mov_b32_e32 v46, v0
	v_mov_b32_e32 v47, v0
	v_mov_b32_e32 v56, v0
	v_mov_b32_e32 v57, v0
	v_mov_b32_e32 v58, v0
	v_mov_b32_e32 v59, v0
	v_mov_b32_e32 v60, v0
	v_mov_b32_e32 v61, v0
	v_mov_b32_e32 v62, v0
	v_mov_b32_e32 v63, v0
	v_mov_b32_e32 v64, v0
	v_mov_b32_e32 v65, v0
	v_mov_b32_e32 v66, v0
	v_mov_b32_e32 v67, v0
	v_mov_b32_e32 v68, v0
	v_mov_b32_e32 v69, v0
	v_mov_b32_e32 v70, v0
	v_mov_b32_e32 v71, v0
	v_mov_b32_e32 v80, v0
	v_mov_b32_e32 v81, v0
	v_mov_b32_e32 v82, v0
	v_mov_b32_e32 v83, v0
	v_mov_b32_e32 v84, v0
	v_mov_b32_e32 v85, v0
	v_mov_b32_e32 v86, v0
	v_mov_b32_e32 v87, v0
	v_mov_b32_e32 v96, v0
	v_mov_b32_e32 v97, v0
	v_mov_b32_e32 v98, v0
	v_mov_b32_e32 v99, v0
	v_mov_b32_e32 v100, v0
	v_mov_b32_e32 v101, v0
	v_mov_b32_e32 v102, v0
	v_mov_b32_e32 v103, v0
	v_mov_b32_e32 v112, v0
	v_mov_b32_e32 v113, v0
	v_mov_b32_e32 v114, v0
	v_mov_b32_e32 v115, v0
	v_mov_b32_e32 v116, v0
	v_mov_b32_e32 v117, v0
	v_mov_b32_e32 v118, v0
	v_mov_b32_e32 v119, v0
	v_mov_b32_e32 v72, v0
	v_mov_b32_e32 v73, v0
	v_mov_b32_e32 v74, v0
	v_mov_b32_e32 v75, v0
	v_mov_b32_e32 v76, v0
	v_mov_b32_e32 v77, v0
	v_mov_b32_e32 v78, v0
	v_mov_b32_e32 v79, v0
	v_mov_b32_e32 v88, v0
	v_mov_b32_e32 v89, v0
	v_mov_b32_e32 v90, v0
	v_mov_b32_e32 v91, v0
	v_mov_b32_e32 v92, v0
	v_mov_b32_e32 v93, v0
	v_mov_b32_e32 v94, v0
	v_mov_b32_e32 v95, v0
	v_mov_b32_e32 v104, v0
	v_mov_b32_e32 v105, v0
	v_mov_b32_e32 v106, v0
	v_mov_b32_e32 v107, v0
	v_mov_b32_e32 v108, v0
	v_mov_b32_e32 v109, v0
	v_mov_b32_e32 v110, v0
	v_mov_b32_e32 v111, v0
	v_mov_b32_e32 v120, v0
	v_mov_b32_e32 v121, v0
	v_mov_b32_e32 v122, v0
	v_mov_b32_e32 v123, v0
	v_mov_b32_e32 v124, v0
	v_mov_b32_e32 v125, v0
	v_mov_b32_e32 v126, v0
	v_mov_b32_e32 v127, v0
	.p2align 6

.LBB0_1054:
	v_mov_b32_e32 v199, 0
	s_andn2_b64 vcc, exec, s[16:17]
	v_mov_b32_e32 v198, 0
	v_mov_b32_e32 v201, 0
	v_mov_b32_e32 v200, 0
	v_mov_b32_e32 v203, 0
	v_mov_b32_e32 v202, 0
	v_mov_b32_e32 v205, 0
	v_mov_b32_e32 v204, 0
	v_mov_b32_e32 v193, 0
	v_mov_b32_e32 v192, 0
	v_mov_b32_e32 v191, 0
	v_mov_b32_e32 v190, 0
	v_mov_b32_e32 v189, 0
	v_mov_b32_e32 v188, 0
	v_mov_b32_e32 v187, 0
	v_mov_b32_e32 v186, 0
	v_mov_b32_e32 v177, 0
	v_mov_b32_e32 v176, 0
	v_mov_b32_e32 v175, 0
	v_mov_b32_e32 v174, 0
	v_mov_b32_e32 v173, 0
	v_mov_b32_e32 v172, 0
	v_mov_b32_e32 v171, 0
	v_mov_b32_e32 v170, 0
	v_mov_b32_e32 v161, 0
	v_mov_b32_e32 v160, 0
	v_mov_b32_e32 v159, 0
	v_mov_b32_e32 v158, 0
	v_mov_b32_e32 v157, 0
	v_mov_b32_e32 v156, 0
	v_mov_b32_e32 v155, 0
	v_mov_b32_e32 v154, 0
	v_mov_b32_e32 v209, 0
	v_mov_b32_e32 v208, 0
	v_mov_b32_e32 v207, 0
	v_mov_b32_e32 v206, 0
	v_mov_b32_e32 v197, 0
	v_mov_b32_e32 v196, 0
	v_mov_b32_e32 v195, 0
	v_mov_b32_e32 v194, 0
	v_mov_b32_e32 v185, 0
	v_mov_b32_e32 v184, 0
	v_mov_b32_e32 v183, 0
	v_mov_b32_e32 v182, 0
	v_mov_b32_e32 v181, 0
	v_mov_b32_e32 v180, 0
	v_mov_b32_e32 v179, 0
	v_mov_b32_e32 v178, 0
	v_mov_b32_e32 v169, 0
	v_mov_b32_e32 v168, 0
	v_mov_b32_e32 v167, 0
	v_mov_b32_e32 v166, 0
	v_mov_b32_e32 v165, 0
	v_mov_b32_e32 v164, 0
	v_mov_b32_e32 v163, 0
	v_mov_b32_e32 v162, 0
	v_mov_b32_e32 v153, 0
	v_mov_b32_e32 v152, 0
	v_mov_b32_e32 v151, 0
	v_mov_b32_e32 v150, 0
	v_mov_b32_e32 v149, 0
	v_mov_b32_e32 v148, 0
	v_mov_b32_e32 v147, 0
	v_mov_b32_e32 v146, 0
	v_mov_b32_e32 v143, 0
	v_mov_b32_e32 v142, 0
	v_mov_b32_e32 v141, 0
	v_mov_b32_e32 v140, 0
	v_mov_b32_e32 v127, 0
	v_mov_b32_e32 v126, 0
	v_mov_b32_e32 v125, 0
	v_mov_b32_e32 v124, 0
	v_mov_b32_e32 v115, 0
	v_mov_b32_e32 v114, 0
	v_mov_b32_e32 v113, 0
	v_mov_b32_e32 v112, 0
	v_mov_b32_e32 v111, 0
	v_mov_b32_e32 v110, 0
	v_mov_b32_e32 v109, 0
	v_mov_b32_e32 v108, 0
	v_mov_b32_e32 v99, 0
	v_mov_b32_e32 v98, 0
	v_mov_b32_e32 v97, 0
	v_mov_b32_e32 v96, 0
	v_mov_b32_e32 v95, 0
	v_mov_b32_e32 v94, 0
	v_mov_b32_e32 v93, 0
	v_mov_b32_e32 v92, 0
	v_mov_b32_e32 v83, 0
	v_mov_b32_e32 v82, 0
	v_mov_b32_e32 v81, 0
	v_mov_b32_e32 v80, 0
	v_mov_b32_e32 v79, 0
	v_mov_b32_e32 v78, 0
	v_mov_b32_e32 v77, 0
	v_mov_b32_e32 v76, 0
	v_mov_b32_e32 v123, 0
	v_mov_b32_e32 v122, 0
	v_mov_b32_e32 v121, 0
	v_mov_b32_e32 v120, 0
	v_mov_b32_e32 v119, 0
	v_mov_b32_e32 v118, 0
	v_mov_b32_e32 v117, 0
	v_mov_b32_e32 v116, 0
	v_mov_b32_e32 v107, 0
	v_mov_b32_e32 v106, 0
	v_mov_b32_e32 v105, 0
	v_mov_b32_e32 v104, 0
	v_mov_b32_e32 v103, 0
	v_mov_b32_e32 v102, 0
	v_mov_b32_e32 v101, 0
	v_mov_b32_e32 v100, 0
	v_mov_b32_e32 v91, 0
	v_mov_b32_e32 v90, 0
	v_mov_b32_e32 v89, 0
	v_mov_b32_e32 v88, 0
	v_mov_b32_e32 v87, 0
	v_mov_b32_e32 v86, 0
	v_mov_b32_e32 v85, 0
	v_mov_b32_e32 v84, 0
	v_mov_b32_e32 v75, 0
	v_mov_b32_e32 v74, 0
	v_mov_b32_e32 v73, 0
	v_mov_b32_e32 v72, 0
	v_mov_b32_e32 v71, 0
	v_mov_b32_e32 v70, 0
	v_mov_b32_e32 v69, 0
	v_mov_b32_e32 v68, 0
	s_cbranch_vccnz .LBB0_1058
	s_add_u32 s24, s24, 0xc000
	s_addc_u32 s25, s25, 0
	s_add_u32 s60, s26, 0x10000
	v_mov_b32_e32 v0, 0
	s_addc_u32 s61, s27, 0
	s_mov_b32 s26, 0
	s_waitcnt lgkmcnt(0)
	v_mov_b32_e32 v1, v0
	v_mov_b32_e32 v2, v0
	v_mov_b32_e32 v3, v0
	v_mov_b32_e32 v4, v0
	v_mov_b32_e32 v5, v0
	v_mov_b32_e32 v6, v0
	v_mov_b32_e32 v7, v0
	v_mov_b32_e32 v8, v0
	v_mov_b32_e32 v9, v0
	v_mov_b32_e32 v10, v0
	v_mov_b32_e32 v11, v0
	v_mov_b32_e32 v12, v0
	v_mov_b32_e32 v13, v0
	v_mov_b32_e32 v14, v0
	v_mov_b32_e32 v15, v0
	v_mov_b32_e32 v20, v0
	v_mov_b32_e32 v21, v0
	v_mov_b32_e32 v22, v0
	v_mov_b32_e32 v23, v0
	v_mov_b32_e32 v28, v0
	v_mov_b32_e32 v29, v0
	v_mov_b32_e32 v30, v0
	v_mov_b32_e32 v31, v0
	v_mov_b32_e32 v36, v0
	v_mov_b32_e32 v37, v0
	v_mov_b32_e32 v38, v0
	v_mov_b32_e32 v39, v0
	v_mov_b32_e32 v44, v0
	v_mov_b32_e32 v45, v0
	v_mov_b32_e32 v46, v0
	v_mov_b32_e32 v47, v0
	v_mov_b32_e32 v16, v0
	v_mov_b32_e32 v17, v0
	v_mov_b32_e32 v18, v0
	v_mov_b32_e32 v19, v0
	v_mov_b32_e32 v24, v0
	v_mov_b32_e32 v25, v0
	v_mov_b32_e32 v26, v0
	v_mov_b32_e32 v27, v0
	v_mov_b32_e32 v32, v0
	v_mov_b32_e32 v33, v0
	v_mov_b32_e32 v34, v0
	v_mov_b32_e32 v35, v0
	v_mov_b32_e32 v40, v0
	v_mov_b32_e32 v41, v0
	v_mov_b32_e32 v42, v0
	v_mov_b32_e32 v43, v0
	v_mov_b32_e32 v48, v0
	v_mov_b32_e32 v49, v0
	v_mov_b32_e32 v50, v0
	v_mov_b32_e32 v51, v0
	v_mov_b32_e32 v52, v0
	v_mov_b32_e32 v53, v0
	v_mov_b32_e32 v54, v0
	v_mov_b32_e32 v55, v0
	v_mov_b32_e32 v56, v0
	v_mov_b32_e32 v57, v0
	v_mov_b32_e32 v58, v0
	v_mov_b32_e32 v59, v0
	v_mov_b32_e32 v60, v0
	v_mov_b32_e32 v61, v0
	v_mov_b32_e32 v62, v0
	v_mov_b32_e32 v63, v0
	v_mov_b32_e32 v64, v0
	v_mov_b32_e32 v65, v0
	v_mov_b32_e32 v66, v0
	v_mov_b32_e32 v67, v0
	v_mov_b32_e32 v68, v0
	v_mov_b32_e32 v69, v0
	v_mov_b32_e32 v70, v0
	v_mov_b32_e32 v71, v0
	v_mov_b32_e32 v72, v0
	v_mov_b32_e32 v73, v0
	v_mov_b32_e32 v74, v0
	v_mov_b32_e32 v75, v0
	v_mov_b32_e32 v76, v0
	v_mov_b32_e32 v77, v0
	v_mov_b32_e32 v78, v0
	v_mov_b32_e32 v79, v0
	v_mov_b32_e32 v84, v0
	v_mov_b32_e32 v85, v0
	v_mov_b32_e32 v86, v0
	v_mov_b32_e32 v87, v0
	v_mov_b32_e32 v92, v0
	v_mov_b32_e32 v93, v0
	v_mov_b32_e32 v94, v0
	v_mov_b32_e32 v95, v0
	v_mov_b32_e32 v100, v0
	v_mov_b32_e32 v101, v0
	v_mov_b32_e32 v102, v0
	v_mov_b32_e32 v103, v0
	v_mov_b32_e32 v108, v0
	v_mov_b32_e32 v109, v0
	v_mov_b32_e32 v110, v0
	v_mov_b32_e32 v111, v0
	v_mov_b32_e32 v80, v0
	v_mov_b32_e32 v81, v0
	v_mov_b32_e32 v82, v0
	v_mov_b32_e32 v83, v0
	v_mov_b32_e32 v88, v0
	v_mov_b32_e32 v89, v0
	v_mov_b32_e32 v90, v0
	v_mov_b32_e32 v91, v0
	v_mov_b32_e32 v96, v0
	v_mov_b32_e32 v97, v0
	v_mov_b32_e32 v98, v0
	v_mov_b32_e32 v99, v0
	v_mov_b32_e32 v104, v0
	v_mov_b32_e32 v105, v0
	v_mov_b32_e32 v106, v0
	v_mov_b32_e32 v107, v0
	v_mov_b32_e32 v112, v0
	v_mov_b32_e32 v113, v0
	v_mov_b32_e32 v114, v0
	v_mov_b32_e32 v115, v0
	v_mov_b32_e32 v116, v0
	v_mov_b32_e32 v117, v0
	v_mov_b32_e32 v118, v0
	v_mov_b32_e32 v119, v0
	v_mov_b32_e32 v120, v0
	v_mov_b32_e32 v121, v0
	v_mov_b32_e32 v122, v0
	v_mov_b32_e32 v123, v0
	v_mov_b32_e32 v124, v0
	v_mov_b32_e32 v125, v0
	v_mov_b32_e32 v126, v0
	v_mov_b32_e32 v127, v0
	.p2align 6

.LBB0_1157:
	v_mov_b32_e32 v127, 0
	s_andn2_b64 vcc, exec, s[22:23]
	v_mov_b32_e32 v126, v127
	v_mov_b32_e32 v125, v127
	v_mov_b32_e32 v124, v127
	v_mov_b32_e32 v123, v127
	v_mov_b32_e32 v122, v127
	v_mov_b32_e32 v121, v127
	v_mov_b32_e32 v120, v127
	v_mov_b32_e32 v111, v127
	v_mov_b32_e32 v110, v127
	v_mov_b32_e32 v109, v127
	v_mov_b32_e32 v108, v127
	v_mov_b32_e32 v107, v127
	v_mov_b32_e32 v106, v127
	v_mov_b32_e32 v105, v127
	v_mov_b32_e32 v104, v127
	v_mov_b32_e32 v95, v127
	v_mov_b32_e32 v94, v127
	v_mov_b32_e32 v93, v127
	v_mov_b32_e32 v92, v127
	v_mov_b32_e32 v91, v127
	v_mov_b32_e32 v90, v127
	v_mov_b32_e32 v89, v127
	v_mov_b32_e32 v88, v127
	v_mov_b32_e32 v79, v127
	v_mov_b32_e32 v78, v127
	v_mov_b32_e32 v77, v127
	v_mov_b32_e32 v76, v127
	v_mov_b32_e32 v75, v127
	v_mov_b32_e32 v74, v127
	v_mov_b32_e32 v73, v127
	v_mov_b32_e32 v72, v127
	v_mov_b32_e32 v119, v127
	v_mov_b32_e32 v118, v127
	v_mov_b32_e32 v117, v127
	v_mov_b32_e32 v116, v127
	v_mov_b32_e32 v115, v127
	v_mov_b32_e32 v114, v127
	v_mov_b32_e32 v113, v127
	v_mov_b32_e32 v112, v127
	v_mov_b32_e32 v103, v127
	v_mov_b32_e32 v102, v127
	v_mov_b32_e32 v101, v127
	v_mov_b32_e32 v100, v127
	v_mov_b32_e32 v99, v127
	v_mov_b32_e32 v98, v127
	v_mov_b32_e32 v97, v127
	v_mov_b32_e32 v96, v127
	v_mov_b32_e32 v87, v127
	v_mov_b32_e32 v86, v127
	v_mov_b32_e32 v85, v127
	v_mov_b32_e32 v84, v127
	v_mov_b32_e32 v83, v127
	v_mov_b32_e32 v82, v127
	v_mov_b32_e32 v81, v127
	v_mov_b32_e32 v80, v127
	v_mov_b32_e32 v71, v127
	v_mov_b32_e32 v70, v127
	v_mov_b32_e32 v69, v127
	v_mov_b32_e32 v68, v127
	v_mov_b32_e32 v67, v127
	v_mov_b32_e32 v66, v127
	v_mov_b32_e32 v65, v127
	v_mov_b32_e32 v64, v127
	v_mov_b32_e32 v63, v127
	v_mov_b32_e32 v62, v127
	v_mov_b32_e32 v61, v127
	v_mov_b32_e32 v60, v127
	v_mov_b32_e32 v59, v127
	v_mov_b32_e32 v58, v127
	v_mov_b32_e32 v57, v127
	v_mov_b32_e32 v56, v127
	v_mov_b32_e32 v47, v127
	v_mov_b32_e32 v46, v127
	v_mov_b32_e32 v45, v127
	v_mov_b32_e32 v44, v127
	v_mov_b32_e32 v43, v127
	v_mov_b32_e32 v42, v127
	v_mov_b32_e32 v41, v127
	v_mov_b32_e32 v40, v127
	v_mov_b32_e32 v31, v127
	v_mov_b32_e32 v30, v127
	v_mov_b32_e32 v29, v127
	v_mov_b32_e32 v28, v127
	v_mov_b32_e32 v27, v127
	v_mov_b32_e32 v26, v127
	v_mov_b32_e32 v25, v127
	v_mov_b32_e32 v24, v127
	v_mov_b32_e32 v15, v127
	v_mov_b32_e32 v14, v127
	v_mov_b32_e32 v13, v127
	v_mov_b32_e32 v12, v127
	v_mov_b32_e32 v11, v127
	v_mov_b32_e32 v10, v127
	v_mov_b32_e32 v9, v127
	v_mov_b32_e32 v8, v127
	v_mov_b32_e32 v55, v127
	v_mov_b32_e32 v54, v127
	v_mov_b32_e32 v53, v127
	v_mov_b32_e32 v52, v127
	v_mov_b32_e32 v51, v127
	v_mov_b32_e32 v50, v127
	v_mov_b32_e32 v49, v127
	v_mov_b32_e32 v48, v127
	v_mov_b32_e32 v39, v127
	v_mov_b32_e32 v38, v127
	v_mov_b32_e32 v37, v127
	v_mov_b32_e32 v36, v127
	v_mov_b32_e32 v35, v127
	v_mov_b32_e32 v34, v127
	v_mov_b32_e32 v33, v127
	v_mov_b32_e32 v32, v127
	v_mov_b32_e32 v23, v127
	v_mov_b32_e32 v22, v127
	v_mov_b32_e32 v21, v127
	v_mov_b32_e32 v20, v127
	v_mov_b32_e32 v19, v127
	v_mov_b32_e32 v18, v127
	v_mov_b32_e32 v17, v127
	v_mov_b32_e32 v16, v127
	v_mov_b32_e32 v7, v127
	v_mov_b32_e32 v6, v127
	v_mov_b32_e32 v5, v127
	v_mov_b32_e32 v4, v127
	v_mov_b32_e32 v3, v127
	v_mov_b32_e32 v2, v127
	v_mov_b32_e32 v1, v127
	v_mov_b32_e32 v0, v127
	s_cbranch_vccnz .LBB0_1160
	s_add_u32 s0, s38, 0x80
	s_addc_u32 s1, s39, 0
	s_add_u32 s38, s6, 0x100
	v_mov_b32_e32 v0, 0
	s_addc_u32 s39, s7, 0
	s_mov_b32 s6, 0
	v_mov_b32_e32 v1, v0
	v_mov_b32_e32 v2, v0
	v_mov_b32_e32 v3, v0
	v_mov_b32_e32 v4, v0
	v_mov_b32_e32 v5, v0
	v_mov_b32_e32 v6, v0
	v_mov_b32_e32 v7, v0
	v_mov_b32_e32 v16, v0
	v_mov_b32_e32 v17, v0
	v_mov_b32_e32 v18, v0
	v_mov_b32_e32 v19, v0
	v_mov_b32_e32 v20, v0
	v_mov_b32_e32 v21, v0
	v_mov_b32_e32 v22, v0
	v_mov_b32_e32 v23, v0
	v_mov_b32_e32 v32, v0
	v_mov_b32_e32 v33, v0
	v_mov_b32_e32 v34, v0
	v_mov_b32_e32 v35, v0
	v_mov_b32_e32 v36, v0
	v_mov_b32_e32 v37, v0
	v_mov_b32_e32 v38, v0
	v_mov_b32_e32 v39, v0
	v_mov_b32_e32 v48, v0
	v_mov_b32_e32 v49, v0
	v_mov_b32_e32 v50, v0
	v_mov_b32_e32 v51, v0
	v_mov_b32_e32 v52, v0
	v_mov_b32_e32 v53, v0
	v_mov_b32_e32 v54, v0
	v_mov_b32_e32 v55, v0
	v_mov_b32_e32 v8, v0
	v_mov_b32_e32 v9, v0
	v_mov_b32_e32 v10, v0
	v_mov_b32_e32 v11, v0
	v_mov_b32_e32 v12, v0
	v_mov_b32_e32 v13, v0
	v_mov_b32_e32 v14, v0
	v_mov_b32_e32 v15, v0
	v_mov_b32_e32 v24, v0
	v_mov_b32_e32 v25, v0
	v_mov_b32_e32 v26, v0
	v_mov_b32_e32 v27, v0
	v_mov_b32_e32 v28, v0
	v_mov_b32_e32 v29, v0
	v_mov_b32_e32 v30, v0
	v_mov_b32_e32 v31, v0
	v_mov_b32_e32 v40, v0
	v_mov_b32_e32 v41, v0
	v_mov_b32_e32 v42, v0
	v_mov_b32_e32 v43, v0
	v_mov_b32_e32 v44, v0
	v_mov_b32_e32 v45, v0
	v_mov_b32_e32 v46, v0
	v_mov_b32_e32 v47, v0
	v_mov_b32_e32 v56, v0
	v_mov_b32_e32 v57, v0
	v_mov_b32_e32 v58, v0
	v_mov_b32_e32 v59, v0
	v_mov_b32_e32 v60, v0
	v_mov_b32_e32 v61, v0
	v_mov_b32_e32 v62, v0
	v_mov_b32_e32 v63, v0
	v_mov_b32_e32 v64, v0
	v_mov_b32_e32 v65, v0
	v_mov_b32_e32 v66, v0
	v_mov_b32_e32 v67, v0
	v_mov_b32_e32 v68, v0
	v_mov_b32_e32 v69, v0
	v_mov_b32_e32 v70, v0
	v_mov_b32_e32 v71, v0
	v_mov_b32_e32 v80, v0
	v_mov_b32_e32 v81, v0
	v_mov_b32_e32 v82, v0
	v_mov_b32_e32 v83, v0
	v_mov_b32_e32 v84, v0
	v_mov_b32_e32 v85, v0
	v_mov_b32_e32 v86, v0
	v_mov_b32_e32 v87, v0
	v_mov_b32_e32 v96, v0
	v_mov_b32_e32 v97, v0
	v_mov_b32_e32 v98, v0
	v_mov_b32_e32 v99, v0
	v_mov_b32_e32 v100, v0
	v_mov_b32_e32 v101, v0
	v_mov_b32_e32 v102, v0
	v_mov_b32_e32 v103, v0
	v_mov_b32_e32 v112, v0
	v_mov_b32_e32 v113, v0
	v_mov_b32_e32 v114, v0
	v_mov_b32_e32 v115, v0
	v_mov_b32_e32 v116, v0
	v_mov_b32_e32 v117, v0
	v_mov_b32_e32 v118, v0
	v_mov_b32_e32 v119, v0
	v_mov_b32_e32 v72, v0
	v_mov_b32_e32 v73, v0
	v_mov_b32_e32 v74, v0
	v_mov_b32_e32 v75, v0
	v_mov_b32_e32 v76, v0
	v_mov_b32_e32 v77, v0
	v_mov_b32_e32 v78, v0
	v_mov_b32_e32 v79, v0
	v_mov_b32_e32 v88, v0
	v_mov_b32_e32 v89, v0
	v_mov_b32_e32 v90, v0
	v_mov_b32_e32 v91, v0
	v_mov_b32_e32 v92, v0
	v_mov_b32_e32 v93, v0
	v_mov_b32_e32 v94, v0
	v_mov_b32_e32 v95, v0
	v_mov_b32_e32 v104, v0
	v_mov_b32_e32 v105, v0
	v_mov_b32_e32 v106, v0
	v_mov_b32_e32 v107, v0
	v_mov_b32_e32 v108, v0
	v_mov_b32_e32 v109, v0
	v_mov_b32_e32 v110, v0
	v_mov_b32_e32 v111, v0
	v_mov_b32_e32 v120, v0
	v_mov_b32_e32 v121, v0
	v_mov_b32_e32 v122, v0
	v_mov_b32_e32 v123, v0
	v_mov_b32_e32 v124, v0
	v_mov_b32_e32 v125, v0
	v_mov_b32_e32 v126, v0
	v_mov_b32_e32 v127, v0
	.p2align 6
